# attention: packed f32 VALU + staging interleaved into exp block; LDS-DMA ring K-loop for the phase-8 ctx pre-pass
# speedup vs baseline: 1.1122x; 1.0028x over previous
; template <bool BNN, class AL, class BL>
; __device__ __forceinline__ void gemm_tile(const AL& al, const BL& bl, int K, u16* smem, f32x16 (&acc)[2][2]) {
;     ...
;   G_LOAD(ra0, rb0, 0)
;   G_STORE(ra0, rb0, 0)
;   if (nkt > 1) G_LOAD(ra1, rb1, 1)
;   __syncthreads();
;   for (int kt = 0; kt < nkt; kt += 2) {
;     if (kt + 2 < nkt) G_LOAD(ra0, rb0, kt + 2)
;     G_COMPUTE(0)
;     if (kt + 1 < nkt) G_STORE(ra1, rb1, 1)
;     __syncthreads();
; __device__ __forceinline__ void gemm_swiglu_phase(const u16* A, const u16* Bt, u16* C, int Mt, u16* smem, u16* smv = nullptr) {
;     ...
;     for (int t = VBID; t < nS; t += VGRID) {
;       const int ms = t / NtS, ns = t - ms * NtS;
;       const u16* Ab = A + (long)(N_X + ms * 128) * 1024;
;       const u16* Bb = Bt + (long)ns * 128 * 1024;
;       auto al = [=](int r, int k) { return ldg16(Ab + (unsigned)(r * 1024 + k)); };
;       auto bl = [=](int r, int k) { return ldg16(Bb + (unsigned)(r * 1024 + k)); };
;       f32x16 acc[2][2];
;       gemm_tile<false>(al, bl, 1024, smv, acc);
.LBB0_1014:
	s_waitcnt vmcnt(0)
	s_barrier
	v_readfirstlane_b32 s98, v153
	v_bfe_u32 v108, v152, 6, 2
	v_readlane_b32 s100, v252, 0
	v_readlane_b32 s101, v252, 1
	v_readfirstlane_b32 s99, v108
	s_nop 3
	s_sub_u32 s100, s100, 0x170
	s_subb_u32 s101, s101, 0
	s_lshl_b32 vcc_lo, s2, 1
	s_add_u32 vcc_lo, vcc_lo, s98
	s_mul_i32 vcc_hi, vcc_lo, 1490
	s_lshr_b32 vcc_hi, vcc_hi, 16
	s_mul_i32 m0, vcc_hi, 44
	s_sub_u32 vcc_lo, vcc_lo, m0
	v_mul_u32_u24_e32 v108, 0x12000, v153
	v_add_u32_e32 v108, 16, v108
	v_and_b32_e32 v109, 31, v152
	v_bfe_u32 v110, v152, 2, 2
	v_bfe_u32 v111, v152, 5, 1
	v_xor_b32_e32 v112, v111, v110
	v_lshlrev_b32_e32 v112, 4, v112
	v_xor_b32_e32 v113, 32, v112
	v_bfe_u32 v114, v152, 7, 1
	v_lshl_add_u32 v114, v114, 6, v109
	v_lshl_add_u32 v114, v114, 6, v108
	v_bfe_u32 v115, v152, 6, 1
	v_lshl_add_u32 v115, v115, 6, v109
	v_lshl_add_u32 v115, v115, 6, v108
	v_add_u32_e32 v104, v114, v112
	v_add_u32_e32 v105, v114, v113
	v_add_u32_e32 v115, 0x2000, v115
	v_add_u32_e32 v106, v115, v112
	v_add_u32_e32 v107, v115, v113
	v_bfe_u32 v109, v152, 2, 4
	v_bfe_u32 v110, v152, 4, 2
	v_and_b32_e32 v111, 3, v152
	v_xor_b32_e32 v110, v111, v110
	v_bfe_u32 v111, v152, 6, 2
	v_lshl_add_u32 v109, v111, 5, v109
	s_mov_b32 m0, 0x800
	v_mul_lo_u32 v112, v109, m0
	v_lshl_add_u32 v112, v110, 4, v112
	s_lshl_b32 s98, s98, 0
	s_mov_b32 s99, s99
	s_lshl_b32 vcc_hi, vcc_hi, 8
	s_or_b32 s98, s98, vcc_hi
	s_lshl_b32 vcc_lo, vcc_lo, 16
	s_or_b32 s98, s98, vcc_lo
	s_load_dwordx2 s[100:101], s[100:101], 0x140
	s_bfe_u32 m0, s98, 0x80008
	s_lshl_b32 m0, m0, 7
	s_add_u32 m0, m0, 0x8000
	s_mul_i32 m0, m0, 0x800
	s_waitcnt lgkmcnt(0)
	s_add_u32 s100, s100, m0
	s_addc_u32 s101, s101, 0
	v_mov_b32_e32 v113, s101
	v_add_co_u32_e32 v96, vcc, s100, v112
	s_nop 1
	v_addc_co_u32_e32 v97, vcc, 0, v113, vcc
	v_add_co_u32_e32 v98, vcc, 0x8000, v96
	s_nop 1
	v_addc_co_u32_e32 v99, vcc, 0, v97, vcc
	v_readlane_b32 s100, v252, 0
	v_readlane_b32 s101, v252, 1
	s_nop 3
	s_sub_u32 s100, s100, 0x170
	s_subb_u32 s101, s101, 0
	s_load_dwordx2 s[100:101], s[100:101], 0xf0
	s_bfe_u32 m0, s98, 0x80010
	s_lshl_b32 m0, m0, 7
	s_mul_i32 m0, m0, 0x800
	s_waitcnt lgkmcnt(0)
	s_add_u32 s100, s100, m0
	s_addc_u32 s101, s101, 0
	v_mov_b32_e32 v113, s101
	v_add_co_u32_e32 v100, vcc, s100, v112
	s_nop 1
	v_addc_co_u32_e32 v101, vcc, 0, v113, vcc
	v_add_co_u32_e32 v102, vcc, 0x8000, v100
	s_nop 1
	v_addc_co_u32_e32 v103, vcc, 0, v101, vcc
	s_and_b32 m0, s98, 1
	s_mul_i32 m0, m0, 0x12000
	s_lshl_b32 s99, s99, 11
	s_add_u32 s98, m0, s99
	s_add_u32 s98, s98, 16
	s_add_u32 m0, s98, 0x0
	s_nop 0
	global_load_lds_dwordx4 v[96:97], off
	s_add_u32 m0, s98, 0x400
	s_nop 0
	global_load_lds_dwordx4 v[98:99], off
	s_add_u32 m0, s98, 0x2000
	s_nop 0
	global_load_lds_dwordx4 v[100:101], off
	s_add_u32 m0, s98, 0x2400
	s_nop 0
	global_load_lds_dwordx4 v[102:103], off
	v_lshl_add_u64 v[96:97], v[96:97], 0, 64
	v_lshl_add_u64 v[98:99], v[98:99], 0, 64
	v_lshl_add_u64 v[100:101], v[100:101], 0, 64
	v_lshl_add_u64 v[102:103], v[102:103], 0, 64
	s_add_u32 m0, s98, 0x4000
	s_nop 0
	global_load_lds_dwordx4 v[96:97], off
	s_add_u32 m0, s98, 0x4400
	s_nop 0
	global_load_lds_dwordx4 v[98:99], off
	s_add_u32 m0, s98, 0x6000
	s_nop 0
	global_load_lds_dwordx4 v[100:101], off
	s_add_u32 m0, s98, 0x6400
	s_nop 0
	global_load_lds_dwordx4 v[102:103], off
	v_lshl_add_u64 v[96:97], v[96:97], 0, 64
	v_lshl_add_u64 v[98:99], v[98:99], 0, 64
	v_lshl_add_u64 v[100:101], v[100:101], 0, 64
	v_lshl_add_u64 v[102:103], v[102:103], 0, 64
	s_add_u32 m0, s98, 0x8000
	s_nop 0
	global_load_lds_dwordx4 v[96:97], off
	s_add_u32 m0, s98, 0x8400
	s_nop 0
	global_load_lds_dwordx4 v[98:99], off
	s_add_u32 m0, s98, 0xa000
	s_nop 0
	global_load_lds_dwordx4 v[100:101], off
	s_add_u32 m0, s98, 0xa400
	s_nop 0
	global_load_lds_dwordx4 v[102:103], off
	v_lshl_add_u64 v[96:97], v[96:97], 0, 64
	v_lshl_add_u64 v[98:99], v[98:99], 0, 64
	v_lshl_add_u64 v[100:101], v[100:101], 0, 64
	v_lshl_add_u64 v[102:103], v[102:103], 0, 64
	s_waitcnt vmcnt(8)
	s_barrier
	ds_read_b128 v[64:67], v104 offset:0
	ds_read_b128 v[68:71], v104 offset:2048
	ds_read_b128 v[72:75], v106 offset:0
	ds_read_b128 v[76:79], v106 offset:2048
	s_add_u32 m0, s98, 0xc000
	s_nop 0
	global_load_lds_dwordx4 v[96:97], off
	s_add_u32 m0, s98, 0xc400
	s_nop 0
	global_load_lds_dwordx4 v[98:99], off
	s_add_u32 m0, s98, 0xe000
	s_nop 0
	global_load_lds_dwordx4 v[100:101], off
	s_add_u32 m0, s98, 0xe400
	s_nop 0
	global_load_lds_dwordx4 v[102:103], off
	v_lshl_add_u64 v[96:97], v[96:97], 0, 64
	v_lshl_add_u64 v[98:99], v[98:99], 0, 64
	v_lshl_add_u64 v[100:101], v[100:101], 0, 64
	v_lshl_add_u64 v[102:103], v[102:103], 0, 64
	s_waitcnt lgkmcnt(0)
	v_mfma_f32_32x32x16_bf16 v[48:63], v[64:67], v[72:75], v[48:63]
	ds_read_b128 v[80:83], v105 offset:0
	v_mfma_f32_32x32x16_bf16 v[32:47], v[64:67], v[76:79], v[32:47]
	ds_read_b128 v[84:87], v105 offset:2048
	v_mfma_f32_32x32x16_bf16 v[16:31], v[68:71], v[72:75], v[16:31]
	ds_read_b128 v[88:91], v107 offset:0
	v_mfma_f32_32x32x16_bf16 v[0:15], v[68:71], v[76:79], v[0:15]
	ds_read_b128 v[92:95], v107 offset:2048
	s_waitcnt vmcnt(8)
	s_waitcnt lgkmcnt(0)
	s_barrier
; template <bool BNN, class AL, class BL>
; __device__ __forceinline__ void gemm_tile(const AL& al, const BL& bl, int K, u16* smem, f32x16 (&acc)[2][2]) {
;     ...
;   G_LOAD(ra0, rb0, 0)
;   G_STORE(ra0, rb0, 0)
;   if (nkt > 1) G_LOAD(ra1, rb1, 1)
;   __syncthreads();
;   for (int kt = 0; kt < nkt; kt += 2) {
;     if (kt + 2 < nkt) G_LOAD(ra0, rb0, kt + 2)
;     G_COMPUTE(0)
;     if (kt + 1 < nkt) G_STORE(ra1, rb1, 1)
;     __syncthreads();
;     if (kt + 1 >= nkt) break;
;     if (kt + 3 < nkt) G_LOAD(ra1, rb1, kt + 3)
;     G_COMPUTE(1)
;     if (kt + 2 < nkt) G_STORE(ra0, rb0, 0)
;     __syncthreads();
;   }
	ds_read_b128 v[64:67], v104 offset:16384
	ds_read_b128 v[68:71], v104 offset:18432
	ds_read_b128 v[72:75], v106 offset:16384
	ds_read_b128 v[76:79], v106 offset:18432
	s_add_u32 m0, s98, 0x0
	v_mfma_f32_32x32x16_bf16 v[48:63], v[80:83], v[88:91], v[48:63]
	global_load_lds_dwordx4 v[96:97], off
	s_add_u32 m0, s98, 0x400
	v_mfma_f32_32x32x16_bf16 v[32:47], v[80:83], v[92:95], v[32:47]
	global_load_lds_dwordx4 v[98:99], off
	s_add_u32 m0, s98, 0x2000
	v_mfma_f32_32x32x16_bf16 v[16:31], v[84:87], v[88:91], v[16:31]
	global_load_lds_dwordx4 v[100:101], off
	s_add_u32 m0, s98, 0x2400
	v_mfma_f32_32x32x16_bf16 v[0:15], v[84:87], v[92:95], v[0:15]
	global_load_lds_dwordx4 v[102:103], off
	v_lshl_add_u64 v[96:97], v[96:97], 0, 64
	v_lshl_add_u64 v[98:99], v[98:99], 0, 64
	v_lshl_add_u64 v[100:101], v[100:101], 0, 64
	v_lshl_add_u64 v[102:103], v[102:103], 0, 64
	s_waitcnt lgkmcnt(0)
	v_mfma_f32_32x32x16_bf16 v[48:63], v[64:67], v[72:75], v[48:63]
	ds_read_b128 v[80:83], v105 offset:16384
	v_mfma_f32_32x32x16_bf16 v[32:47], v[64:67], v[76:79], v[32:47]
	ds_read_b128 v[84:87], v105 offset:18432
	v_mfma_f32_32x32x16_bf16 v[16:31], v[68:71], v[72:75], v[16:31]
	ds_read_b128 v[88:91], v107 offset:16384
	v_mfma_f32_32x32x16_bf16 v[0:15], v[68:71], v[76:79], v[0:15]
	ds_read_b128 v[92:95], v107 offset:18432
	s_waitcnt vmcnt(8)
	s_waitcnt lgkmcnt(0)
	s_barrier
	ds_read_b128 v[64:67], v104 offset:32768
	ds_read_b128 v[68:71], v104 offset:34816
	ds_read_b128 v[72:75], v106 offset:32768
	ds_read_b128 v[76:79], v106 offset:34816
	s_add_u32 m0, s98, 0x4000
	v_mfma_f32_32x32x16_bf16 v[48:63], v[80:83], v[88:91], v[48:63]
	global_load_lds_dwordx4 v[96:97], off
	s_add_u32 m0, s98, 0x4400
	v_mfma_f32_32x32x16_bf16 v[32:47], v[80:83], v[92:95], v[32:47]
	global_load_lds_dwordx4 v[98:99], off
	s_add_u32 m0, s98, 0x6000
	v_mfma_f32_32x32x16_bf16 v[16:31], v[84:87], v[88:91], v[16:31]
	global_load_lds_dwordx4 v[100:101], off
	s_add_u32 m0, s98, 0x6400
	v_mfma_f32_32x32x16_bf16 v[0:15], v[84:87], v[92:95], v[0:15]
	global_load_lds_dwordx4 v[102:103], off
	v_lshl_add_u64 v[96:97], v[96:97], 0, 64
	v_lshl_add_u64 v[98:99], v[98:99], 0, 64
	v_lshl_add_u64 v[100:101], v[100:101], 0, 64
	v_lshl_add_u64 v[102:103], v[102:103], 0, 64
	s_waitcnt lgkmcnt(0)
	v_mfma_f32_32x32x16_bf16 v[48:63], v[64:67], v[72:75], v[48:63]
	ds_read_b128 v[80:83], v105 offset:32768
	v_mfma_f32_32x32x16_bf16 v[32:47], v[64:67], v[76:79], v[32:47]
	ds_read_b128 v[84:87], v105 offset:34816
	v_mfma_f32_32x32x16_bf16 v[16:31], v[68:71], v[72:75], v[16:31]
	ds_read_b128 v[88:91], v107 offset:32768
	v_mfma_f32_32x32x16_bf16 v[0:15], v[68:71], v[76:79], v[0:15]
	ds_read_b128 v[92:95], v107 offset:34816
	s_waitcnt vmcnt(8)
	s_waitcnt lgkmcnt(0)
	s_barrier
	ds_read_b128 v[64:67], v104 offset:49152
	ds_read_b128 v[68:71], v104 offset:51200
	ds_read_b128 v[72:75], v106 offset:49152
	ds_read_b128 v[76:79], v106 offset:51200
	s_add_u32 m0, s98, 0x8000
	v_mfma_f32_32x32x16_bf16 v[48:63], v[80:83], v[88:91], v[48:63]
	global_load_lds_dwordx4 v[96:97], off
	s_add_u32 m0, s98, 0x8400
	v_mfma_f32_32x32x16_bf16 v[32:47], v[80:83], v[92:95], v[32:47]
	global_load_lds_dwordx4 v[98:99], off
	s_add_u32 m0, s98, 0xa000
	v_mfma_f32_32x32x16_bf16 v[16:31], v[84:87], v[88:91], v[16:31]
	global_load_lds_dwordx4 v[100:101], off
	s_add_u32 m0, s98, 0xa400
	v_mfma_f32_32x32x16_bf16 v[0:15], v[84:87], v[92:95], v[0:15]
	global_load_lds_dwordx4 v[102:103], off
	v_lshl_add_u64 v[96:97], v[96:97], 0, 64
	v_lshl_add_u64 v[98:99], v[98:99], 0, 64
	v_lshl_add_u64 v[100:101], v[100:101], 0, 64
	v_lshl_add_u64 v[102:103], v[102:103], 0, 64
	s_waitcnt lgkmcnt(0)
	v_mfma_f32_32x32x16_bf16 v[48:63], v[64:67], v[72:75], v[48:63]
	ds_read_b128 v[80:83], v105 offset:49152
	v_mfma_f32_32x32x16_bf16 v[32:47], v[64:67], v[76:79], v[32:47]
	ds_read_b128 v[84:87], v105 offset:51200
	v_mfma_f32_32x32x16_bf16 v[16:31], v[68:71], v[72:75], v[16:31]
	ds_read_b128 v[88:91], v107 offset:49152
	v_mfma_f32_32x32x16_bf16 v[0:15], v[68:71], v[76:79], v[0:15]
	ds_read_b128 v[92:95], v107 offset:51200
	s_waitcnt vmcnt(8)
	s_waitcnt lgkmcnt(0)
	s_mov_b32 s99, 6
.Lmy_pre_p2_loop:
	s_barrier
	ds_read_b128 v[64:67], v104 offset:0
	ds_read_b128 v[68:71], v104 offset:2048
	ds_read_b128 v[72:75], v106 offset:0
	ds_read_b128 v[76:79], v106 offset:2048
	s_add_u32 m0, s98, 0xc000
	v_mfma_f32_32x32x16_bf16 v[48:63], v[80:83], v[88:91], v[48:63]
	global_load_lds_dwordx4 v[96:97], off
	s_add_u32 m0, s98, 0xc400
	v_mfma_f32_32x32x16_bf16 v[32:47], v[80:83], v[92:95], v[32:47]
	global_load_lds_dwordx4 v[98:99], off
	s_add_u32 m0, s98, 0xe000
	v_mfma_f32_32x32x16_bf16 v[16:31], v[84:87], v[88:91], v[16:31]
	global_load_lds_dwordx4 v[100:101], off
	s_add_u32 m0, s98, 0xe400
	v_mfma_f32_32x32x16_bf16 v[0:15], v[84:87], v[92:95], v[0:15]
	global_load_lds_dwordx4 v[102:103], off
	v_lshl_add_u64 v[96:97], v[96:97], 0, 64
	v_lshl_add_u64 v[98:99], v[98:99], 0, 64
	v_lshl_add_u64 v[100:101], v[100:101], 0, 64
	v_lshl_add_u64 v[102:103], v[102:103], 0, 64
	s_waitcnt lgkmcnt(0)
	v_mfma_f32_32x32x16_bf16 v[48:63], v[64:67], v[72:75], v[48:63]
	ds_read_b128 v[80:83], v105 offset:0
	v_mfma_f32_32x32x16_bf16 v[32:47], v[64:67], v[76:79], v[32:47]
	ds_read_b128 v[84:87], v105 offset:2048
	v_mfma_f32_32x32x16_bf16 v[16:31], v[68:71], v[72:75], v[16:31]
	ds_read_b128 v[88:91], v107 offset:0
	v_mfma_f32_32x32x16_bf16 v[0:15], v[68:71], v[76:79], v[0:15]
	ds_read_b128 v[92:95], v107 offset:2048
	s_waitcnt vmcnt(8)
	s_waitcnt lgkmcnt(0)
	s_barrier
; template <bool BNN, class AL, class BL>
; __device__ __forceinline__ void gemm_tile(const AL& al, const BL& bl, int K, u16* smem, f32x16 (&acc)[2][2]) {
;     ...
;   G_LOAD(ra0, rb0, 0)
;   G_STORE(ra0, rb0, 0)
;   if (nkt > 1) G_LOAD(ra1, rb1, 1)
;   __syncthreads();
;   for (int kt = 0; kt < nkt; kt += 2) {
;     if (kt + 2 < nkt) G_LOAD(ra0, rb0, kt + 2)
;     G_COMPUTE(0)
;     if (kt + 1 < nkt) G_STORE(ra1, rb1, 1)
;     __syncthreads();
;     if (kt + 1 >= nkt) break;
;     if (kt + 3 < nkt) G_LOAD(ra1, rb1, kt + 3)
;     G_COMPUTE(1)
;     if (kt + 2 < nkt) G_STORE(ra0, rb0, 0)
;     __syncthreads();
;   }
	ds_read_b128 v[64:67], v104 offset:16384
	ds_read_b128 v[68:71], v104 offset:18432
	ds_read_b128 v[72:75], v106 offset:16384
	ds_read_b128 v[76:79], v106 offset:18432
	s_add_u32 m0, s98, 0x0
	v_mfma_f32_32x32x16_bf16 v[48:63], v[80:83], v[88:91], v[48:63]
	global_load_lds_dwordx4 v[96:97], off
	s_add_u32 m0, s98, 0x400
	v_mfma_f32_32x32x16_bf16 v[32:47], v[80:83], v[92:95], v[32:47]
	global_load_lds_dwordx4 v[98:99], off
	s_add_u32 m0, s98, 0x2000
	v_mfma_f32_32x32x16_bf16 v[16:31], v[84:87], v[88:91], v[16:31]
	global_load_lds_dwordx4 v[100:101], off
	s_add_u32 m0, s98, 0x2400
	v_mfma_f32_32x32x16_bf16 v[0:15], v[84:87], v[92:95], v[0:15]
	global_load_lds_dwordx4 v[102:103], off
	v_lshl_add_u64 v[96:97], v[96:97], 0, 64
	v_lshl_add_u64 v[98:99], v[98:99], 0, 64
	v_lshl_add_u64 v[100:101], v[100:101], 0, 64
	v_lshl_add_u64 v[102:103], v[102:103], 0, 64
	s_waitcnt lgkmcnt(0)
	v_mfma_f32_32x32x16_bf16 v[48:63], v[64:67], v[72:75], v[48:63]
	ds_read_b128 v[80:83], v105 offset:16384
	v_mfma_f32_32x32x16_bf16 v[32:47], v[64:67], v[76:79], v[32:47]
	ds_read_b128 v[84:87], v105 offset:18432
	v_mfma_f32_32x32x16_bf16 v[16:31], v[68:71], v[72:75], v[16:31]
	ds_read_b128 v[88:91], v107 offset:16384
	v_mfma_f32_32x32x16_bf16 v[0:15], v[68:71], v[76:79], v[0:15]
	ds_read_b128 v[92:95], v107 offset:18432
	s_waitcnt vmcnt(8)
	s_waitcnt lgkmcnt(0)
	s_barrier
	ds_read_b128 v[64:67], v104 offset:32768
	ds_read_b128 v[68:71], v104 offset:34816
	ds_read_b128 v[72:75], v106 offset:32768
	ds_read_b128 v[76:79], v106 offset:34816
	s_add_u32 m0, s98, 0x4000
	v_mfma_f32_32x32x16_bf16 v[48:63], v[80:83], v[88:91], v[48:63]
	global_load_lds_dwordx4 v[96:97], off
	s_add_u32 m0, s98, 0x4400
	v_mfma_f32_32x32x16_bf16 v[32:47], v[80:83], v[92:95], v[32:47]
	global_load_lds_dwordx4 v[98:99], off
	s_add_u32 m0, s98, 0x6000
	v_mfma_f32_32x32x16_bf16 v[16:31], v[84:87], v[88:91], v[16:31]
	global_load_lds_dwordx4 v[100:101], off
	s_add_u32 m0, s98, 0x6400
	v_mfma_f32_32x32x16_bf16 v[0:15], v[84:87], v[92:95], v[0:15]
	global_load_lds_dwordx4 v[102:103], off
	v_lshl_add_u64 v[96:97], v[96:97], 0, 64
	v_lshl_add_u64 v[98:99], v[98:99], 0, 64
	v_lshl_add_u64 v[100:101], v[100:101], 0, 64
	v_lshl_add_u64 v[102:103], v[102:103], 0, 64
	s_waitcnt lgkmcnt(0)
	v_mfma_f32_32x32x16_bf16 v[48:63], v[64:67], v[72:75], v[48:63]
	ds_read_b128 v[80:83], v105 offset:32768
	v_mfma_f32_32x32x16_bf16 v[32:47], v[64:67], v[76:79], v[32:47]
	ds_read_b128 v[84:87], v105 offset:34816
	v_mfma_f32_32x32x16_bf16 v[16:31], v[68:71], v[72:75], v[16:31]
	ds_read_b128 v[88:91], v107 offset:32768
	v_mfma_f32_32x32x16_bf16 v[0:15], v[68:71], v[76:79], v[0:15]
	ds_read_b128 v[92:95], v107 offset:34816
	s_waitcnt vmcnt(8)
	s_waitcnt lgkmcnt(0)
	s_barrier
	ds_read_b128 v[64:67], v104 offset:49152
	ds_read_b128 v[68:71], v104 offset:51200
	ds_read_b128 v[72:75], v106 offset:49152
	ds_read_b128 v[76:79], v106 offset:51200
	s_add_u32 m0, s98, 0x8000
	v_mfma_f32_32x32x16_bf16 v[48:63], v[80:83], v[88:91], v[48:63]
	global_load_lds_dwordx4 v[96:97], off
	s_add_u32 m0, s98, 0x8400
	v_mfma_f32_32x32x16_bf16 v[32:47], v[80:83], v[92:95], v[32:47]
	global_load_lds_dwordx4 v[98:99], off
	s_add_u32 m0, s98, 0xa000
	v_mfma_f32_32x32x16_bf16 v[16:31], v[84:87], v[88:91], v[16:31]
	global_load_lds_dwordx4 v[100:101], off
	s_add_u32 m0, s98, 0xa400
	v_mfma_f32_32x32x16_bf16 v[0:15], v[84:87], v[92:95], v[0:15]
	global_load_lds_dwordx4 v[102:103], off
	v_lshl_add_u64 v[96:97], v[96:97], 0, 64
	v_lshl_add_u64 v[98:99], v[98:99], 0, 64
	v_lshl_add_u64 v[100:101], v[100:101], 0, 64
	v_lshl_add_u64 v[102:103], v[102:103], 0, 64
	s_waitcnt lgkmcnt(0)
	v_mfma_f32_32x32x16_bf16 v[48:63], v[64:67], v[72:75], v[48:63]
	ds_read_b128 v[80:83], v105 offset:49152
	v_mfma_f32_32x32x16_bf16 v[32:47], v[64:67], v[76:79], v[32:47]
	ds_read_b128 v[84:87], v105 offset:51200
	v_mfma_f32_32x32x16_bf16 v[16:31], v[68:71], v[72:75], v[16:31]
	ds_read_b128 v[88:91], v107 offset:49152
	v_mfma_f32_32x32x16_bf16 v[0:15], v[68:71], v[76:79], v[0:15]
	ds_read_b128 v[92:95], v107 offset:51200
	s_waitcnt vmcnt(8)
	s_waitcnt lgkmcnt(0)
	s_sub_u32 s99, s99, 1
	s_cmp_lg_u32 s99, 0
	s_cbranch_scc1 .Lmy_pre_p2_loop
	s_barrier
; template <bool BNN, class AL, class BL>
; __device__ __forceinline__ void gemm_tile(const AL& al, const BL& bl, int K, u16* smem, f32x16 (&acc)[2][2]) {
;     ...
;   G_LOAD(ra0, rb0, 0)
;   G_STORE(ra0, rb0, 0)
;   if (nkt > 1) G_LOAD(ra1, rb1, 1)
;   __syncthreads();
;   for (int kt = 0; kt < nkt; kt += 2) {
;     if (kt + 2 < nkt) G_LOAD(ra0, rb0, kt + 2)
;     G_COMPUTE(0)
;     if (kt + 1 < nkt) G_STORE(ra1, rb1, 1)
;     __syncthreads();
;     if (kt + 1 >= nkt) break;
;     if (kt + 3 < nkt) G_LOAD(ra1, rb1, kt + 3)
;     G_COMPUTE(1)
;     if (kt + 2 < nkt) G_STORE(ra0, rb0, 0)
;     __syncthreads();
;   }
	ds_read_b128 v[64:67], v104 offset:0
	ds_read_b128 v[68:71], v104 offset:2048
	ds_read_b128 v[72:75], v106 offset:0
	ds_read_b128 v[76:79], v106 offset:2048
	s_add_u32 m0, s98, 0xc000
	v_mfma_f32_32x32x16_bf16 v[48:63], v[80:83], v[88:91], v[48:63]
	global_load_lds_dwordx4 v[96:97], off
	s_add_u32 m0, s98, 0xc400
	v_mfma_f32_32x32x16_bf16 v[32:47], v[80:83], v[92:95], v[32:47]
	global_load_lds_dwordx4 v[98:99], off
	s_add_u32 m0, s98, 0xe000
	v_mfma_f32_32x32x16_bf16 v[16:31], v[84:87], v[88:91], v[16:31]
	global_load_lds_dwordx4 v[100:101], off
	s_add_u32 m0, s98, 0xe400
	v_mfma_f32_32x32x16_bf16 v[0:15], v[84:87], v[92:95], v[0:15]
	global_load_lds_dwordx4 v[102:103], off
	v_lshl_add_u64 v[96:97], v[96:97], 0, 64
	v_lshl_add_u64 v[98:99], v[98:99], 0, 64
	v_lshl_add_u64 v[100:101], v[100:101], 0, 64
	v_lshl_add_u64 v[102:103], v[102:103], 0, 64
	s_waitcnt lgkmcnt(0)
	v_mfma_f32_32x32x16_bf16 v[48:63], v[64:67], v[72:75], v[48:63]
	ds_read_b128 v[80:83], v105 offset:0
	v_mfma_f32_32x32x16_bf16 v[32:47], v[64:67], v[76:79], v[32:47]
	ds_read_b128 v[84:87], v105 offset:2048
	v_mfma_f32_32x32x16_bf16 v[16:31], v[68:71], v[72:75], v[16:31]
	ds_read_b128 v[88:91], v107 offset:0
	v_mfma_f32_32x32x16_bf16 v[0:15], v[68:71], v[76:79], v[0:15]
	ds_read_b128 v[92:95], v107 offset:2048
	s_waitcnt vmcnt(8)
	s_waitcnt lgkmcnt(0)
	s_barrier
	ds_read_b128 v[64:67], v104 offset:16384
	ds_read_b128 v[68:71], v104 offset:18432
	ds_read_b128 v[72:75], v106 offset:16384
	ds_read_b128 v[76:79], v106 offset:18432
	v_mfma_f32_32x32x16_bf16 v[48:63], v[80:83], v[88:91], v[48:63]
	v_mfma_f32_32x32x16_bf16 v[32:47], v[80:83], v[92:95], v[32:47]
	v_mfma_f32_32x32x16_bf16 v[16:31], v[84:87], v[88:91], v[16:31]
	v_mfma_f32_32x32x16_bf16 v[0:15], v[84:87], v[92:95], v[0:15]
	s_waitcnt lgkmcnt(0)
	v_mfma_f32_32x32x16_bf16 v[48:63], v[64:67], v[72:75], v[48:63]
	ds_read_b128 v[80:83], v105 offset:16384
	v_mfma_f32_32x32x16_bf16 v[32:47], v[64:67], v[76:79], v[32:47]
	ds_read_b128 v[84:87], v105 offset:18432
	v_mfma_f32_32x32x16_bf16 v[16:31], v[68:71], v[72:75], v[16:31]
	ds_read_b128 v[88:91], v107 offset:16384
	v_mfma_f32_32x32x16_bf16 v[0:15], v[68:71], v[76:79], v[0:15]
	ds_read_b128 v[92:95], v107 offset:18432
	s_waitcnt vmcnt(4)
	s_waitcnt lgkmcnt(0)
	s_barrier
	ds_read_b128 v[64:67], v104 offset:32768
	ds_read_b128 v[68:71], v104 offset:34816
	ds_read_b128 v[72:75], v106 offset:32768
	ds_read_b128 v[76:79], v106 offset:34816
	v_mfma_f32_32x32x16_bf16 v[48:63], v[80:83], v[88:91], v[48:63]
	v_mfma_f32_32x32x16_bf16 v[32:47], v[80:83], v[92:95], v[32:47]
	v_mfma_f32_32x32x16_bf16 v[16:31], v[84:87], v[88:91], v[16:31]
	v_mfma_f32_32x32x16_bf16 v[0:15], v[84:87], v[92:95], v[0:15]
	s_waitcnt lgkmcnt(0)
	v_mfma_f32_32x32x16_bf16 v[48:63], v[64:67], v[72:75], v[48:63]
	ds_read_b128 v[80:83], v105 offset:32768
	v_mfma_f32_32x32x16_bf16 v[32:47], v[64:67], v[76:79], v[32:47]
	ds_read_b128 v[84:87], v105 offset:34816
	v_mfma_f32_32x32x16_bf16 v[16:31], v[68:71], v[72:75], v[16:31]
	ds_read_b128 v[88:91], v107 offset:32768
	v_mfma_f32_32x32x16_bf16 v[0:15], v[68:71], v[76:79], v[0:15]
	ds_read_b128 v[92:95], v107 offset:34816
	s_waitcnt vmcnt(0)
	s_waitcnt lgkmcnt(0)
	s_barrier
	ds_read_b128 v[64:67], v104 offset:49152
	ds_read_b128 v[68:71], v104 offset:51200
	ds_read_b128 v[72:75], v106 offset:49152
	ds_read_b128 v[76:79], v106 offset:51200
	v_mfma_f32_32x32x16_bf16 v[48:63], v[80:83], v[88:91], v[48:63]
	v_mfma_f32_32x32x16_bf16 v[32:47], v[80:83], v[92:95], v[32:47]
	v_mfma_f32_32x32x16_bf16 v[16:31], v[84:87], v[88:91], v[16:31]
	v_mfma_f32_32x32x16_bf16 v[0:15], v[84:87], v[92:95], v[0:15]
	s_waitcnt lgkmcnt(0)
	v_mfma_f32_32x32x16_bf16 v[48:63], v[64:67], v[72:75], v[48:63]
	ds_read_b128 v[80:83], v105 offset:49152
	v_mfma_f32_32x32x16_bf16 v[32:47], v[64:67], v[76:79], v[32:47]
	ds_read_b128 v[84:87], v105 offset:51200
	v_mfma_f32_32x32x16_bf16 v[16:31], v[68:71], v[72:75], v[16:31]
	ds_read_b128 v[88:91], v107 offset:49152
	v_mfma_f32_32x32x16_bf16 v[0:15], v[68:71], v[76:79], v[0:15]
	ds_read_b128 v[92:95], v107 offset:51200
	s_waitcnt lgkmcnt(0)
	v_mfma_f32_32x32x16_bf16 v[48:63], v[80:83], v[88:91], v[48:63]
	v_mfma_f32_32x32x16_bf16 v[32:47], v[80:83], v[92:95], v[32:47]
	v_mfma_f32_32x32x16_bf16 v[16:31], v[84:87], v[88:91], v[16:31]
	v_mfma_f32_32x32x16_bf16 v[0:15], v[84:87], v[92:95], v[0:15]
	s_nop 15
	s_barrier
	s_branch .LBB0_1011

; __device__ __forceinline__ void attn_phase(const Params& P, char* smem_raw) {
;     ...
;     for (int ck = 0; ck < 6; ++ck) {
;       int lane_c = lane;
;       asm volatile("" : "+v"(lane_c));
;       __syncthreads();
; #pragma unroll
;       for (int i = 0; i < 4; ++i) {
;         const int idx = tid + 256 * i;
;         *reinterpret_cast<uint4*>(&sm_k[(idx >> 3) * LDSS + (idx & 7) * 8]) = kreg[i];
;         *reinterpret_cast<uint4*>(&sm_vt[(idx >> 4) * 136 + (idx & 15) * 8]) = vreg[i];
;       }
;       __syncthreads();
;       f32x4 sacc[8];
; #pragma unroll
;       for (int t8 = 0; t8 < 8; ++t8) sacc[t8] = f32x4{0.f, 0.f, 0.f, 0.f};
; #pragma unroll
;       for (int s = 0; s < 2; ++s)
; #pragma unroll
;         for (int t8 = 0; t8 < 8; ++t8) {
;           const bf16x8 kf = *reinterpret_cast<const bf16x8*>(&sm_k[(t8 * 16 + (lane_c & 15)) * LDSS + s * 32 + (lane_c >> 4) * 8]);
;           sacc[t8] = __builtin_amdgcn_mfma_f32_16x16x32_bf16(qf[s], kf, sacc[t8], 0, 0, 0);
;         }
;       if (ck < 5) {
;         ATT_ISSUE(t, ck + 1)
;       } else if (t + VGRID < 8192) {
;         ATT_ISSUE(t + VGRID, 0)
;         ATT_QLOAD(t + VGRID)
;       }
;       if (ck < 4) {
;         const float* rb0 = sm_rpb + (rs + ck * 2 - r + 7) * 31;
; #pragma unroll
;         for (int t8 = 0; t8 < 8; ++t8)
; #pragma unroll
;           for (int reg = 0; reg < 4; ++reg)
;             sacc[t8][reg] += rb0[(t8 >> 2) * 31 + dco[reg][t8 & 3]];
;       }
; #pragma unroll
;       for (int reg = 0; reg < 4; ++reg) {
;         float mx = sacc[0][reg];
; #pragma unroll
;         for (int t8 = 1; t8 < 8; ++t8) mx = fmaxf(mx, sacc[t8][reg]);
;         mx = row16_max(mx);
;         const float mnew = fmaxf(mrow[reg], mx);
;         const float alpha = __builtin_amdgcn_exp2f(mrow[reg] - mnew);
;         mrow[reg] = mnew;
;         float rsum = 0.f;
; #pragma unroll
;         for (int t8 = 0; t8 < 8; ++t8) {
;           const float p = __builtin_amdgcn_exp2f(sacc[t8][reg] - mnew);
;           rsum += p;
;           sm_p[(wid * 16 + (lane_c >> 4) * 4 + reg) * 136 + t8 * 16 + (lane_c & 15)] = f2bf(p);
;         }
;         rsum = row16_sum(rsum);
;         lrow[reg] = lrow[reg] * alpha + rsum;
; #pragma unroll
;         for (int td = 0; td < 4; ++td) o[td][reg] *= alpha;
;       }
.Lmy_att_tile:
	s_barrier
	ds_read_b128 v[112:115], v144 offset:0
	ds_read_b128 v[116:119], v145 offset:0
	ds_read_b128 v[120:123], v144 offset:512
	ds_read_b128 v[124:127], v145 offset:512
	ds_read_b128 v[128:131], v144 offset:4096
	ds_read_b128 v[132:135], v145 offset:4096
	ds_read_b128 v[136:139], v144 offset:4608
	ds_read_b128 v[140:143], v145 offset:4608
	s_waitcnt lgkmcnt(7)
	v_mfma_f32_16x16x32_bf16 v[0:3], v[112:115], v[64:67], v[0:3]
	ds_read_b128 v[112:115], v144 offset:8192
	s_waitcnt lgkmcnt(7)
	v_mfma_f32_16x16x32_bf16 v[0:3], v[116:119], v[68:71], v[0:3]
	ds_read_b128 v[116:119], v145 offset:8192
	s_waitcnt lgkmcnt(7)
	v_mfma_f32_16x16x32_bf16 v[4:7], v[120:123], v[64:67], v[4:7]
	ds_read_b128 v[120:123], v144 offset:8704
	s_waitcnt lgkmcnt(7)
	v_mfma_f32_16x16x32_bf16 v[4:7], v[124:127], v[68:71], v[4:7]
	ds_read_b128 v[124:127], v145 offset:8704
	s_waitcnt lgkmcnt(7)
	v_mfma_f32_16x16x32_bf16 v[8:11], v[128:131], v[64:67], v[8:11]
	ds_read_b128 v[128:131], v144 offset:12288
	s_waitcnt lgkmcnt(7)
	v_mfma_f32_16x16x32_bf16 v[8:11], v[132:135], v[68:71], v[8:11]
	ds_read_b128 v[132:135], v145 offset:12288
	s_waitcnt lgkmcnt(7)
	v_mfma_f32_16x16x32_bf16 v[12:15], v[136:139], v[64:67], v[12:15]
	ds_read_b128 v[136:139], v144 offset:12800
	s_waitcnt lgkmcnt(7)
	v_mfma_f32_16x16x32_bf16 v[12:15], v[140:143], v[68:71], v[12:15]
	ds_read_b128 v[140:143], v145 offset:12800
	s_waitcnt lgkmcnt(7)
	v_mfma_f32_16x16x32_bf16 v[16:19], v[112:115], v[64:67], v[16:19]
	s_waitcnt lgkmcnt(6)
	v_mfma_f32_16x16x32_bf16 v[16:19], v[116:119], v[68:71], v[16:19]
	s_waitcnt lgkmcnt(5)
	v_mfma_f32_16x16x32_bf16 v[20:23], v[120:123], v[64:67], v[20:23]
	s_waitcnt lgkmcnt(4)
	v_mfma_f32_16x16x32_bf16 v[20:23], v[124:127], v[68:71], v[20:23]
	s_waitcnt lgkmcnt(3)
	v_mfma_f32_16x16x32_bf16 v[24:27], v[128:131], v[64:67], v[24:27]
	s_waitcnt lgkmcnt(2)
	v_mfma_f32_16x16x32_bf16 v[24:27], v[132:135], v[68:71], v[24:27]
	s_waitcnt lgkmcnt(1)
	v_mfma_f32_16x16x32_bf16 v[28:31], v[136:139], v[64:67], v[28:31]
	s_waitcnt lgkmcnt(0)
	v_mfma_f32_16x16x32_bf16 v[28:31], v[140:143], v[68:71], v[28:31]
	s_nop 7
	v_max3_f32 v203, v0, v1, v2
	v_max3_f32 v203, v203, v3, v4
	v_max3_f32 v203, v203, v5, v6
	v_max3_f32 v203, v203, v7, v8
	v_max3_f32 v203, v203, v9, v10
	v_max3_f32 v203, v203, v11, v12
	v_max3_f32 v203, v203, v13, v14
	v_max3_f32 v203, v203, v15, v16
	v_max3_f32 v203, v203, v17, v18
	v_max3_f32 v203, v203, v19, v20
	v_max3_f32 v203, v203, v21, v22
	v_max3_f32 v203, v203, v23, v24
	v_max3_f32 v203, v203, v25, v26
	v_max3_f32 v203, v203, v27, v28
	v_max3_f32 v203, v203, v29, v30
	v_max_f32_e32 v203, v203, v31
	v_mov_b32_e32 v205, v203
	s_nop 1
	v_permlane16_swap_b32_e32 v203, v205
	v_max_f32_e32 v203, v203, v205
	v_mov_b32_e32 v205, v203
	s_nop 1
	v_permlane32_swap_b32_e32 v203, v205
	v_max_f32_e32 v203, v203, v205
	v_max_f32_e32 v218, v200, v203
	v_sub_f32_e32 v220, v200, v218
	v_mov_b32_e32 v219, v218
	v_exp_f32_e32 v220, v220
	v_mov_b32_e32 v200, v218
	v_pk_add_f32 v[0:1], v[0:1], v[218:219] neg_lo:[0,1] neg_hi:[0,1]
	v_pk_add_f32 v[2:3], v[2:3], v[218:219] neg_lo:[0,1] neg_hi:[0,1]
	v_pk_add_f32 v[4:5], v[4:5], v[218:219] neg_lo:[0,1] neg_hi:[0,1]
	v_pk_add_f32 v[6:7], v[6:7], v[218:219] neg_lo:[0,1] neg_hi:[0,1]
	v_pk_add_f32 v[8:9], v[8:9], v[218:219] neg_lo:[0,1] neg_hi:[0,1]
	v_pk_add_f32 v[10:11], v[10:11], v[218:219] neg_lo:[0,1] neg_hi:[0,1]
	v_pk_add_f32 v[12:13], v[12:13], v[218:219] neg_lo:[0,1] neg_hi:[0,1]
	v_pk_add_f32 v[14:15], v[14:15], v[218:219] neg_lo:[0,1] neg_hi:[0,1]
	v_pk_add_f32 v[16:17], v[16:17], v[218:219] neg_lo:[0,1] neg_hi:[0,1]
	v_pk_add_f32 v[18:19], v[18:19], v[218:219] neg_lo:[0,1] neg_hi:[0,1]
	v_pk_add_f32 v[20:21], v[20:21], v[218:219] neg_lo:[0,1] neg_hi:[0,1]
	v_pk_add_f32 v[22:23], v[22:23], v[218:219] neg_lo:[0,1] neg_hi:[0,1]
	v_pk_add_f32 v[24:25], v[24:25], v[218:219] neg_lo:[0,1] neg_hi:[0,1]
	v_pk_add_f32 v[26:27], v[26:27], v[218:219] neg_lo:[0,1] neg_hi:[0,1]
	v_pk_add_f32 v[28:29], v[28:29], v[218:219] neg_lo:[0,1] neg_hi:[0,1]
	v_pk_add_f32 v[30:31], v[30:31], v[218:219] neg_lo:[0,1] neg_hi:[0,1]
	v_exp_f32_e32 v0, v0
	s_waitcnt vmcnt(4)
	v_exp_f32_e32 v1, v1
	ds_write_b128 v150, v[80:83] offset:32768
	v_exp_f32_e32 v2, v2
	ds_write_b128 v150, v[84:87] offset:36864
	v_exp_f32_e32 v3, v3
	ds_write_b128 v150, v[88:91] offset:40960
	v_exp_f32_e32 v4, v4
	ds_write_b128 v150, v[92:95] offset:45056
	v_exp_f32_e32 v5, v5
	ds_write_b128 v151, v[96:99] offset:32768
	v_exp_f32_e32 v6, v6
	ds_write_b128 v151, v[100:103] offset:36864
	v_exp_f32_e32 v7, v7
	ds_write_b128 v151, v[104:107] offset:40960
	v_exp_f32_e32 v8, v8
	ds_write_b128 v151, v[108:111] offset:45056
	v_exp_f32_e32 v9, v9
	s_add_u32 s100, s12, 0x180000
	v_exp_f32_e32 v10, v10
	s_addc_u32 s101, s13, 0
	v_exp_f32_e32 v11, v11
	s_add_u32 s0, s14, 0x200
	v_exp_f32_e32 v12, v12
	s_addc_u32 s1, s15, 0
	v_exp_f32_e32 v13, v13
	global_load_dwordx4 v[80:83], v154, s[100:101] offset:2048
	v_exp_f32_e32 v14, v14
	global_load_dwordx4 v[96:99], v158, s[0:1]
	v_exp_f32_e32 v15, v15
	global_load_dwordx4 v[84:87], v155, s[100:101] offset:2048
	v_exp_f32_e32 v16, v16
	global_load_dwordx4 v[100:103], v159, s[0:1]
	v_exp_f32_e32 v17, v17
	global_load_dwordx4 v[88:91], v156, s[100:101] offset:2048
	v_exp_f32_e32 v18, v18
	global_load_dwordx4 v[104:107], v160, s[0:1]
	v_exp_f32_e32 v19, v19
	global_load_dwordx4 v[92:95], v157, s[100:101] offset:2048
	v_exp_f32_e32 v20, v20
	global_load_dwordx4 v[108:111], v161, s[0:1]
	v_exp_f32_e32 v21, v21
	v_exp_f32_e32 v22, v22
	v_exp_f32_e32 v23, v23
	v_exp_f32_e32 v24, v24
	v_exp_f32_e32 v25, v25
	v_exp_f32_e32 v26, v26
; __device__ __forceinline__ void attn_phase(const Params& P, char* smem_raw) {
;     ...
; #pragma unroll
;       for (int reg = 0; reg < 4; ++reg) {
;         float mx = sacc[0][reg];
; #pragma unroll
;         for (int t8 = 1; t8 < 8; ++t8) mx = fmaxf(mx, sacc[t8][reg]);
;         mx = row16_max(mx);
;         const float mnew = fmaxf(mrow[reg], mx);
;         const float alpha = __builtin_amdgcn_exp2f(mrow[reg] - mnew);
;         mrow[reg] = mnew;
;         float rsum = 0.f;
; #pragma unroll
;         for (int t8 = 0; t8 < 8; ++t8) {
;           const float p = __builtin_amdgcn_exp2f(sacc[t8][reg] - mnew);
;           rsum += p;
;           sm_p[(wid * 16 + (lane_c >> 4) * 4 + reg) * 136 + t8 * 16 + (lane_c & 15)] = f2bf(p);
;         }
;         rsum = row16_sum(rsum);
;         lrow[reg] = lrow[reg] * alpha + rsum;
; #pragma unroll
;         for (int td = 0; td < 4; ++td) o[td][reg] *= alpha;
;       }
;       asm volatile("s_waitcnt lgkmcnt(0)" ::: "memory");
; #pragma unroll
;       for (int s4 = 0; s4 < 4; ++s4) {
;         const bf16x8 pf = *reinterpret_cast<const bf16x8*>(&sm_p[(wid * 16 + (lane_c & 15)) * 136 + s4 * 32 + (lane_c >> 4) * 8]);
; #pragma unroll
;         for (int td = 0; td < 4; ++td) {
;           const bf16x8 vf = *reinterpret_cast<const bf16x8*>(&sm_vt[(td * 16 + (lane_c & 15)) * 136 + s4 * 32 + (lane_c >> 4) * 8]);
;           o[td] = __builtin_amdgcn_mfma_f32_16x16x32_bf16(pf, vf, o[td], 0, 0, 0);
;         }
;       }
	v_exp_f32_e32 v27, v27
	v_exp_f32_e32 v28, v28
	v_exp_f32_e32 v29, v29
	v_exp_f32_e32 v30, v30
	v_exp_f32_e32 v31, v31
	s_and_b32 s0, s3, 0xff
	s_lshr_b32 s1, s0, 2
	s_and_b32 s0, s0, 3
	s_lshl_b32 s0, s0, 5
	s_lshr_b32 vcc_lo, s3, 12
	s_add_u32 s0, s0, vcc_lo
	s_sub_i32 vcc_lo, s0, 4
	s_max_i32 vcc_lo, vcc_lo, 0
	s_min_i32 vcc_lo, vcc_lo, 0x78
	s_lshl_b32 vcc_hi, s1, 13
	s_lshl_b32 m0, s1, 8
	s_add_u32 m0, m0, 0x8000
	s_mul_i32 m0, m0, 0x1800
	s_add_u32 s16, s4, m0
	s_addc_u32 s17, s5, 0
	s_lshl_b32 m0, s1, 19
	s_add_u32 s36, s8, m0
	s_addc_u32 s37, s9, 0
	s_lshl_b32 m0, s0, 6
	s_add_u32 m0, m0, vcc_hi
	s_lshl_b32 m0, m0, 11
	s_add_u32 s98, s10, m0
	s_addc_u32 s99, s11, 0
	ds_read_b128 v[112:115], v146 offset:0
	ds_read_b128 v[116:119], v146 offset:4096
	ds_read_b128 v[120:123], v146 offset:8192
	ds_read_b128 v[124:127], v146 offset:12288
	ds_read_b128 v[128:131], v147 offset:0
	ds_read_b128 v[132:135], v147 offset:4096
	ds_read_b128 v[136:139], v147 offset:8192
	ds_read_b128 v[140:143], v147 offset:12288
	v_mov_b32_e32 v221, v220
	v_pk_add_f32 v[222:223], v[0:1], v[2:3]
	v_pk_add_f32 v[222:223], v[222:223], v[4:5]
	v_pk_add_f32 v[222:223], v[222:223], v[6:7]
	v_pk_add_f32 v[222:223], v[222:223], v[8:9]
	v_pk_add_f32 v[222:223], v[222:223], v[10:11]
	v_pk_add_f32 v[222:223], v[222:223], v[12:13]
	v_pk_add_f32 v[222:223], v[222:223], v[14:15]
	v_pk_add_f32 v[222:223], v[222:223], v[16:17]
	v_pk_add_f32 v[222:223], v[222:223], v[18:19]
	v_pk_add_f32 v[222:223], v[222:223], v[20:21]
	v_pk_add_f32 v[222:223], v[222:223], v[22:23]
	v_pk_add_f32 v[222:223], v[222:223], v[24:25]
	v_pk_add_f32 v[222:223], v[222:223], v[26:27]
	v_pk_add_f32 v[222:223], v[222:223], v[28:29]
	v_pk_add_f32 v[222:223], v[222:223], v[30:31]
	v_pk_mul_f32 v[32:33], v[32:33], v[220:221]
	v_pk_mul_f32 v[34:35], v[34:35], v[220:221]
	v_pk_mul_f32 v[36:37], v[36:37], v[220:221]
	v_pk_mul_f32 v[38:39], v[38:39], v[220:221]
	v_pk_mul_f32 v[40:41], v[40:41], v[220:221]
	v_pk_mul_f32 v[42:43], v[42:43], v[220:221]
	v_pk_mul_f32 v[44:45], v[44:45], v[220:221]
	v_pk_mul_f32 v[46:47], v[46:47], v[220:221]
	v_add_f32_e32 v203, v222, v223
	v_fma_f32 v201, v201, v220, v203
	v_cvt_pk_bf16_f32 v48, v0, v1
	v_cvt_pk_bf16_f32 v49, v2, v3
	v_cvt_pk_bf16_f32 v50, v4, v5
	v_cvt_pk_bf16_f32 v51, v6, v7
	v_cvt_pk_bf16_f32 v52, v8, v9
	v_cvt_pk_bf16_f32 v53, v10, v11
	v_cvt_pk_bf16_f32 v54, v12, v13
	v_cvt_pk_bf16_f32 v55, v14, v15
	v_cvt_pk_bf16_f32 v56, v16, v17
	v_cvt_pk_bf16_f32 v57, v18, v19
	v_cvt_pk_bf16_f32 v58, v20, v21
	v_cvt_pk_bf16_f32 v59, v22, v23
	v_cvt_pk_bf16_f32 v60, v24, v25
	v_cvt_pk_bf16_f32 v61, v26, v27
	v_cvt_pk_bf16_f32 v62, v28, v29
	v_cvt_pk_bf16_f32 v63, v30, v31
	s_waitcnt lgkmcnt(7)
	v_mfma_f32_16x16x32_bf16 v[32:35], v[112:115], v[48:51], v[32:35]
	ds_read_b128 v[112:115], v148 offset:0
	s_waitcnt lgkmcnt(7)
	v_mfma_f32_16x16x32_bf16 v[36:39], v[116:119], v[48:51], v[36:39]
	ds_read_b128 v[116:119], v148 offset:4096
	s_waitcnt lgkmcnt(7)
	v_mfma_f32_16x16x32_bf16 v[40:43], v[120:123], v[48:51], v[40:43]
	ds_read_b128 v[120:123], v148 offset:8192
	s_waitcnt lgkmcnt(7)
	v_mfma_f32_16x16x32_bf16 v[44:47], v[124:127], v[48:51], v[44:47]
	ds_read_b128 v[124:127], v148 offset:12288
	s_waitcnt lgkmcnt(7)
	v_mfma_f32_16x16x32_bf16 v[32:35], v[128:131], v[52:55], v[32:35]
	ds_read_b128 v[128:131], v149 offset:0
	s_waitcnt lgkmcnt(7)
	v_mfma_f32_16x16x32_bf16 v[36:39], v[132:135], v[52:55], v[36:39]
	ds_read_b128 v[132:135], v149 offset:4096
	s_waitcnt lgkmcnt(7)
	v_mfma_f32_16x16x32_bf16 v[40:43], v[136:139], v[52:55], v[40:43]
	ds_read_b128 v[136:139], v149 offset:8192
	s_waitcnt lgkmcnt(7)
	v_mfma_f32_16x16x32_bf16 v[44:47], v[140:143], v[52:55], v[44:47]
	ds_read_b128 v[140:143], v149 offset:12288
	s_waitcnt lgkmcnt(7)
	v_mfma_f32_16x16x32_bf16 v[32:35], v[112:115], v[56:59], v[32:35]
	s_waitcnt lgkmcnt(6)
	v_mfma_f32_16x16x32_bf16 v[36:39], v[116:119], v[56:59], v[36:39]
	s_waitcnt lgkmcnt(5)
	v_mfma_f32_16x16x32_bf16 v[40:43], v[120:123], v[56:59], v[40:43]
	s_waitcnt lgkmcnt(4)
	v_mfma_f32_16x16x32_bf16 v[44:47], v[124:127], v[56:59], v[44:47]
	s_waitcnt lgkmcnt(3)
	v_mfma_f32_16x16x32_bf16 v[32:35], v[128:131], v[60:63], v[32:35]
	s_waitcnt lgkmcnt(2)
	v_mfma_f32_16x16x32_bf16 v[36:39], v[132:135], v[60:63], v[36:39]
	s_waitcnt lgkmcnt(1)
	v_mfma_f32_16x16x32_bf16 v[40:43], v[136:139], v[60:63], v[40:43]
	s_waitcnt lgkmcnt(0)
	v_mfma_f32_16x16x32_bf16 v[44:47], v[140:143], v[60:63], v[44:47]
	ds_read_b32 v0, v184 offset:640
	ds_read_b32 v1, v185 offset:640
	ds_read_b32 v2, v186 offset:640
	ds_read_b32 v3, v187 offset:640
	ds_read_b32 v4, v188 offset:640
	ds_read_b32 v5, v189 offset:640
	ds_read_b32 v6, v190 offset:640
	ds_read_b32 v7, v191 offset:640
	ds_read_b32 v8, v192 offset:640
	ds_read_b32 v9, v193 offset:640
	ds_read_b32 v10, v194 offset:640
	ds_read_b32 v11, v195 offset:640
	ds_read_b32 v12, v196 offset:640
	ds_read_b32 v13, v197 offset:640
	ds_read_b32 v14, v198 offset:640
	ds_read_b32 v15, v199 offset:640
	ds_read_b32 v16, v184 offset:768
	ds_read_b32 v17, v185 offset:768
	ds_read_b32 v18, v186 offset:768
	ds_read_b32 v19, v187 offset:768
	ds_read_b32 v20, v188 offset:768
	ds_read_b32 v21, v189 offset:768
	ds_read_b32 v22, v190 offset:768
	ds_read_b32 v23, v191 offset:768
	ds_read_b32 v24, v192 offset:768
	ds_read_b32 v25, v193 offset:768
	ds_read_b32 v26, v194 offset:768
	ds_read_b32 v27, v195 offset:768
	ds_read_b32 v28, v196 offset:768
	ds_read_b32 v29, v197 offset:768
	ds_read_b32 v30, v198 offset:768
	ds_read_b32 v31, v199 offset:768
	s_waitcnt lgkmcnt(0)
	s_barrier
; __device__ __forceinline__ void attn_phase(const Params& P, char* smem_raw) {
;     ...
;     for (int ck = 0; ck < 6; ++ck) {
;       int lane_c = lane;
;       asm volatile("" : "+v"(lane_c));
;       __syncthreads();
; #pragma unroll
;       for (int i = 0; i < 4; ++i) {
;         const int idx = tid + 256 * i;
;         *reinterpret_cast<uint4*>(&sm_k[(idx >> 3) * LDSS + (idx & 7) * 8]) = kreg[i];
;         *reinterpret_cast<uint4*>(&sm_vt[(idx >> 4) * 136 + (idx & 15) * 8]) = vreg[i];
;       }
;       __syncthreads();
;       f32x4 sacc[8];
; #pragma unroll
;       for (int t8 = 0; t8 < 8; ++t8) sacc[t8] = f32x4{0.f, 0.f, 0.f, 0.f};
; #pragma unroll
;       for (int s = 0; s < 2; ++s)
; #pragma unroll
;         for (int t8 = 0; t8 < 8; ++t8) {
;           const bf16x8 kf = *reinterpret_cast<const bf16x8*>(&sm_k[(t8 * 16 + (lane_c & 15)) * LDSS + s * 32 + (lane_c >> 4) * 8]);
;           sacc[t8] = __builtin_amdgcn_mfma_f32_16x16x32_bf16(qf[s], kf, sacc[t8], 0, 0, 0);
;         }
;       if (ck < 5) {
;         ATT_ISSUE(t, ck + 1)
;       } else if (t + VGRID < 8192) {
;         ATT_ISSUE(t + VGRID, 0)
;         ATT_QLOAD(t + VGRID)
;       }
;       if (ck < 4) {
;         const float* rb0 = sm_rpb + (rs + ck * 2 - r + 7) * 31;
; #pragma unroll
;         for (int t8 = 0; t8 < 8; ++t8)
; #pragma unroll
;           for (int reg = 0; reg < 4; ++reg)
;             sacc[t8][reg] += rb0[(t8 >> 2) * 31 + dco[reg][t8 & 3]];
;       }
; #pragma unroll
;       for (int reg = 0; reg < 4; ++reg) {
;         float mx = sacc[0][reg];
; #pragma unroll
;         for (int t8 = 1; t8 < 8; ++t8) mx = fmaxf(mx, sacc[t8][reg]);
;         mx = row16_max(mx);
;         const float mnew = fmaxf(mrow[reg], mx);
;         const float alpha = __builtin_amdgcn_exp2f(mrow[reg] - mnew);
;         mrow[reg] = mnew;
;         float rsum = 0.f;
; #pragma unroll
;         for (int t8 = 0; t8 < 8; ++t8) {
;           const float p = __builtin_amdgcn_exp2f(sacc[t8][reg] - mnew);
;           rsum += p;
;           sm_p[(wid * 16 + (lane_c >> 4) * 4 + reg) * 136 + t8 * 16 + (lane_c & 15)] = f2bf(p);
;         }
;         rsum = row16_sum(rsum);
;         lrow[reg] = lrow[reg] * alpha + rsum;
; #pragma unroll
;         for (int td = 0; td < 4; ++td) o[td][reg] *= alpha;
;       }
	ds_read_b128 v[112:115], v144 offset:32768
	ds_read_b128 v[116:119], v145 offset:32768
	ds_read_b128 v[120:123], v144 offset:33280
	ds_read_b128 v[124:127], v145 offset:33280
	ds_read_b128 v[128:131], v144 offset:36864
	ds_read_b128 v[132:135], v145 offset:36864
	ds_read_b128 v[136:139], v144 offset:37376
	ds_read_b128 v[140:143], v145 offset:37376
	s_waitcnt lgkmcnt(7)
	v_mfma_f32_16x16x32_bf16 v[0:3], v[112:115], v[64:67], v[0:3]
	ds_read_b128 v[112:115], v144 offset:40960
	s_waitcnt lgkmcnt(7)
	v_mfma_f32_16x16x32_bf16 v[0:3], v[116:119], v[68:71], v[0:3]
	ds_read_b128 v[116:119], v145 offset:40960
	s_waitcnt lgkmcnt(7)
	v_mfma_f32_16x16x32_bf16 v[4:7], v[120:123], v[64:67], v[4:7]
	ds_read_b128 v[120:123], v144 offset:41472
	s_waitcnt lgkmcnt(7)
	v_mfma_f32_16x16x32_bf16 v[4:7], v[124:127], v[68:71], v[4:7]
	ds_read_b128 v[124:127], v145 offset:41472
	s_waitcnt lgkmcnt(7)
	v_mfma_f32_16x16x32_bf16 v[8:11], v[128:131], v[64:67], v[8:11]
	ds_read_b128 v[128:131], v144 offset:45056
	s_waitcnt lgkmcnt(7)
	v_mfma_f32_16x16x32_bf16 v[8:11], v[132:135], v[68:71], v[8:11]
	ds_read_b128 v[132:135], v145 offset:45056
	s_waitcnt lgkmcnt(7)
	v_mfma_f32_16x16x32_bf16 v[12:15], v[136:139], v[64:67], v[12:15]
	ds_read_b128 v[136:139], v144 offset:45568
	s_waitcnt lgkmcnt(7)
	v_mfma_f32_16x16x32_bf16 v[12:15], v[140:143], v[68:71], v[12:15]
	ds_read_b128 v[140:143], v145 offset:45568
	s_waitcnt lgkmcnt(7)
	v_mfma_f32_16x16x32_bf16 v[16:19], v[112:115], v[64:67], v[16:19]
	s_waitcnt lgkmcnt(6)
	v_mfma_f32_16x16x32_bf16 v[16:19], v[116:119], v[68:71], v[16:19]
	s_waitcnt lgkmcnt(5)
	v_mfma_f32_16x16x32_bf16 v[20:23], v[120:123], v[64:67], v[20:23]
	s_waitcnt lgkmcnt(4)
	v_mfma_f32_16x16x32_bf16 v[20:23], v[124:127], v[68:71], v[20:23]
	s_waitcnt lgkmcnt(3)
	v_mfma_f32_16x16x32_bf16 v[24:27], v[128:131], v[64:67], v[24:27]
	s_waitcnt lgkmcnt(2)
	v_mfma_f32_16x16x32_bf16 v[24:27], v[132:135], v[68:71], v[24:27]
	s_waitcnt lgkmcnt(1)
	v_mfma_f32_16x16x32_bf16 v[28:31], v[136:139], v[64:67], v[28:31]
	s_waitcnt lgkmcnt(0)
	v_mfma_f32_16x16x32_bf16 v[28:31], v[140:143], v[68:71], v[28:31]
	s_nop 7
	v_max3_f32 v203, v0, v1, v2
	v_max3_f32 v203, v203, v3, v4
	v_max3_f32 v203, v203, v5, v6
	v_max3_f32 v203, v203, v7, v8
	v_max3_f32 v203, v203, v9, v10
	v_max3_f32 v203, v203, v11, v12
	v_max3_f32 v203, v203, v13, v14
	v_max3_f32 v203, v203, v15, v16
	v_max3_f32 v203, v203, v17, v18
	v_max3_f32 v203, v203, v19, v20
	v_max3_f32 v203, v203, v21, v22
	v_max3_f32 v203, v203, v23, v24
	v_max3_f32 v203, v203, v25, v26
	v_max3_f32 v203, v203, v27, v28
	v_max3_f32 v203, v203, v29, v30
	v_max_f32_e32 v203, v203, v31
	v_mov_b32_e32 v205, v203
	s_nop 1
	v_permlane16_swap_b32_e32 v203, v205
	v_max_f32_e32 v203, v203, v205
	v_mov_b32_e32 v205, v203
	s_nop 1
	v_permlane32_swap_b32_e32 v203, v205
	v_max_f32_e32 v203, v203, v205
	v_max_f32_e32 v218, v200, v203
	v_sub_f32_e32 v220, v200, v218
	v_mov_b32_e32 v219, v218
	v_exp_f32_e32 v220, v220
	v_mov_b32_e32 v200, v218
	v_pk_add_f32 v[0:1], v[0:1], v[218:219] neg_lo:[0,1] neg_hi:[0,1]
	v_pk_add_f32 v[2:3], v[2:3], v[218:219] neg_lo:[0,1] neg_hi:[0,1]
	v_pk_add_f32 v[4:5], v[4:5], v[218:219] neg_lo:[0,1] neg_hi:[0,1]
	v_pk_add_f32 v[6:7], v[6:7], v[218:219] neg_lo:[0,1] neg_hi:[0,1]
	v_pk_add_f32 v[8:9], v[8:9], v[218:219] neg_lo:[0,1] neg_hi:[0,1]
	v_pk_add_f32 v[10:11], v[10:11], v[218:219] neg_lo:[0,1] neg_hi:[0,1]
	v_pk_add_f32 v[12:13], v[12:13], v[218:219] neg_lo:[0,1] neg_hi:[0,1]
	v_pk_add_f32 v[14:15], v[14:15], v[218:219] neg_lo:[0,1] neg_hi:[0,1]
	v_pk_add_f32 v[16:17], v[16:17], v[218:219] neg_lo:[0,1] neg_hi:[0,1]
	v_pk_add_f32 v[18:19], v[18:19], v[218:219] neg_lo:[0,1] neg_hi:[0,1]
	v_pk_add_f32 v[20:21], v[20:21], v[218:219] neg_lo:[0,1] neg_hi:[0,1]
	v_pk_add_f32 v[22:23], v[22:23], v[218:219] neg_lo:[0,1] neg_hi:[0,1]
	v_pk_add_f32 v[24:25], v[24:25], v[218:219] neg_lo:[0,1] neg_hi:[0,1]
	v_pk_add_f32 v[26:27], v[26:27], v[218:219] neg_lo:[0,1] neg_hi:[0,1]
	v_pk_add_f32 v[28:29], v[28:29], v[218:219] neg_lo:[0,1] neg_hi:[0,1]
	v_pk_add_f32 v[30:31], v[30:31], v[218:219] neg_lo:[0,1] neg_hi:[0,1]
	v_exp_f32_e32 v0, v0
	s_waitcnt vmcnt(0)
	v_exp_f32_e32 v1, v1
	ds_write_b128 v150, v[80:83] offset:0
	v_exp_f32_e32 v2, v2
	ds_write_b128 v150, v[84:87] offset:4096
	v_exp_f32_e32 v3, v3
	ds_write_b128 v150, v[88:91] offset:8192
	v_exp_f32_e32 v4, v4
	ds_write_b128 v150, v[92:95] offset:12288
	v_exp_f32_e32 v5, v5
	ds_write_b128 v151, v[96:99] offset:0
	v_exp_f32_e32 v6, v6
	ds_write_b128 v151, v[100:103] offset:4096
	v_exp_f32_e32 v7, v7
	ds_write_b128 v151, v[104:107] offset:8192
	v_exp_f32_e32 v8, v8
	ds_write_b128 v151, v[108:111] offset:12288
	v_exp_f32_e32 v9, v9
	s_add_u32 s100, s12, 0x240000
	v_exp_f32_e32 v10, v10
	s_addc_u32 s101, s13, 0
	v_exp_f32_e32 v11, v11
	s_add_u32 s0, s14, 0x300
	v_exp_f32_e32 v12, v12
	s_addc_u32 s1, s15, 0
	v_exp_f32_e32 v13, v13
	global_load_dwordx4 v[80:83], v154, s[100:101] offset:2048
	v_exp_f32_e32 v14, v14
	global_load_dwordx4 v[96:99], v158, s[0:1]
	v_exp_f32_e32 v15, v15
	global_load_dwordx4 v[84:87], v155, s[100:101] offset:2048
	v_exp_f32_e32 v16, v16
	global_load_dwordx4 v[100:103], v159, s[0:1]
	v_exp_f32_e32 v17, v17
	global_load_dwordx4 v[88:91], v156, s[100:101] offset:2048
	v_exp_f32_e32 v18, v18
	global_load_dwordx4 v[104:107], v160, s[0:1]
	v_exp_f32_e32 v19, v19
	global_load_dwordx4 v[92:95], v157, s[100:101] offset:2048
	v_exp_f32_e32 v20, v20
	global_load_dwordx4 v[108:111], v161, s[0:1]
	v_exp_f32_e32 v21, v21
	v_exp_f32_e32 v22, v22
	v_exp_f32_e32 v23, v23
	v_exp_f32_e32 v24, v24
	v_exp_f32_e32 v25, v25
	v_exp_f32_e32 v26, v26
	v_exp_f32_e32 v27, v27
; __device__ __forceinline__ void attn_phase(const Params& P, char* smem_raw) {
;     ...
;       if (ck < 4) {
;         const float* rb0 = sm_rpb + (rs + ck * 2 - r + 7) * 31;
; #pragma unroll
;         for (int t8 = 0; t8 < 8; ++t8)
; #pragma unroll
;           for (int reg = 0; reg < 4; ++reg)
;             sacc[t8][reg] += rb0[(t8 >> 2) * 31 + dco[reg][t8 & 3]];
;       }
; #pragma unroll
;       for (int reg = 0; reg < 4; ++reg) {
;         float mx = sacc[0][reg];
; #pragma unroll
;         for (int t8 = 1; t8 < 8; ++t8) mx = fmaxf(mx, sacc[t8][reg]);
;         mx = row16_max(mx);
;         const float mnew = fmaxf(mrow[reg], mx);
;         const float alpha = __builtin_amdgcn_exp2f(mrow[reg] - mnew);
;         mrow[reg] = mnew;
;         float rsum = 0.f;
; #pragma unroll
;         for (int t8 = 0; t8 < 8; ++t8) {
;           const float p = __builtin_amdgcn_exp2f(sacc[t8][reg] - mnew);
;           rsum += p;
;           sm_p[(wid * 16 + (lane_c >> 4) * 4 + reg) * 136 + t8 * 16 + (lane_c & 15)] = f2bf(p);
;         }
;         rsum = row16_sum(rsum);
;         lrow[reg] = lrow[reg] * alpha + rsum;
; #pragma unroll
;         for (int td = 0; td < 4; ++td) o[td][reg] *= alpha;
;       }
;       asm volatile("s_waitcnt lgkmcnt(0)" ::: "memory");
; #pragma unroll
;       for (int s4 = 0; s4 < 4; ++s4) {
;         const bf16x8 pf = *reinterpret_cast<const bf16x8*>(&sm_p[(wid * 16 + (lane_c & 15)) * 136 + s4 * 32 + (lane_c >> 4) * 8]);
; #pragma unroll
;         for (int td = 0; td < 4; ++td) {
;           const bf16x8 vf = *reinterpret_cast<const bf16x8*>(&sm_vt[(td * 16 + (lane_c & 15)) * 136 + s4 * 32 + (lane_c >> 4) * 8]);
;           o[td] = __builtin_amdgcn_mfma_f32_16x16x32_bf16(pf, vf, o[td], 0, 0, 0);
;         }
;       }
	v_exp_f32_e32 v28, v28
	v_exp_f32_e32 v29, v29
	v_exp_f32_e32 v30, v30
	v_exp_f32_e32 v31, v31
	ds_read_b128 v[112:115], v146 offset:32768
	ds_read_b128 v[116:119], v146 offset:36864
	ds_read_b128 v[120:123], v146 offset:40960
	ds_read_b128 v[124:127], v146 offset:45056
	ds_read_b128 v[128:131], v147 offset:32768
	ds_read_b128 v[132:135], v147 offset:36864
	ds_read_b128 v[136:139], v147 offset:40960
	ds_read_b128 v[140:143], v147 offset:45056
	v_mov_b32_e32 v221, v220
	v_pk_add_f32 v[222:223], v[0:1], v[2:3]
	v_pk_add_f32 v[222:223], v[222:223], v[4:5]
	v_pk_add_f32 v[222:223], v[222:223], v[6:7]
	v_pk_add_f32 v[222:223], v[222:223], v[8:9]
	v_pk_add_f32 v[222:223], v[222:223], v[10:11]
	v_pk_add_f32 v[222:223], v[222:223], v[12:13]
	v_pk_add_f32 v[222:223], v[222:223], v[14:15]
	v_pk_add_f32 v[222:223], v[222:223], v[16:17]
	v_pk_add_f32 v[222:223], v[222:223], v[18:19]
	v_pk_add_f32 v[222:223], v[222:223], v[20:21]
	v_pk_add_f32 v[222:223], v[222:223], v[22:23]
	v_pk_add_f32 v[222:223], v[222:223], v[24:25]
	v_pk_add_f32 v[222:223], v[222:223], v[26:27]
	v_pk_add_f32 v[222:223], v[222:223], v[28:29]
	v_pk_add_f32 v[222:223], v[222:223], v[30:31]
	v_pk_mul_f32 v[32:33], v[32:33], v[220:221]
	v_pk_mul_f32 v[34:35], v[34:35], v[220:221]
	v_pk_mul_f32 v[36:37], v[36:37], v[220:221]
	v_pk_mul_f32 v[38:39], v[38:39], v[220:221]
	v_pk_mul_f32 v[40:41], v[40:41], v[220:221]
	v_pk_mul_f32 v[42:43], v[42:43], v[220:221]
	v_pk_mul_f32 v[44:45], v[44:45], v[220:221]
	v_pk_mul_f32 v[46:47], v[46:47], v[220:221]
	v_add_f32_e32 v203, v222, v223
	v_fma_f32 v201, v201, v220, v203
	v_cvt_pk_bf16_f32 v48, v0, v1
	v_cvt_pk_bf16_f32 v49, v2, v3
	v_cvt_pk_bf16_f32 v50, v4, v5
	v_cvt_pk_bf16_f32 v51, v6, v7
	v_cvt_pk_bf16_f32 v52, v8, v9
	v_cvt_pk_bf16_f32 v53, v10, v11
	v_cvt_pk_bf16_f32 v54, v12, v13
	v_cvt_pk_bf16_f32 v55, v14, v15
	v_cvt_pk_bf16_f32 v56, v16, v17
	v_cvt_pk_bf16_f32 v57, v18, v19
	v_cvt_pk_bf16_f32 v58, v20, v21
	v_cvt_pk_bf16_f32 v59, v22, v23
	v_cvt_pk_bf16_f32 v60, v24, v25
	v_cvt_pk_bf16_f32 v61, v26, v27
	v_cvt_pk_bf16_f32 v62, v28, v29
	v_cvt_pk_bf16_f32 v63, v30, v31
	s_waitcnt lgkmcnt(7)
	v_mfma_f32_16x16x32_bf16 v[32:35], v[112:115], v[48:51], v[32:35]
	ds_read_b128 v[112:115], v148 offset:32768
	s_waitcnt lgkmcnt(7)
	v_mfma_f32_16x16x32_bf16 v[36:39], v[116:119], v[48:51], v[36:39]
	ds_read_b128 v[116:119], v148 offset:36864
	s_waitcnt lgkmcnt(7)
	v_mfma_f32_16x16x32_bf16 v[40:43], v[120:123], v[48:51], v[40:43]
	ds_read_b128 v[120:123], v148 offset:40960
	s_waitcnt lgkmcnt(7)
	v_mfma_f32_16x16x32_bf16 v[44:47], v[124:127], v[48:51], v[44:47]
	ds_read_b128 v[124:127], v148 offset:45056
	s_waitcnt lgkmcnt(7)
	v_mfma_f32_16x16x32_bf16 v[32:35], v[128:131], v[52:55], v[32:35]
	ds_read_b128 v[128:131], v149 offset:32768
	s_waitcnt lgkmcnt(7)
	v_mfma_f32_16x16x32_bf16 v[36:39], v[132:135], v[52:55], v[36:39]
	ds_read_b128 v[132:135], v149 offset:36864
	s_waitcnt lgkmcnt(7)
	v_mfma_f32_16x16x32_bf16 v[40:43], v[136:139], v[52:55], v[40:43]
	ds_read_b128 v[136:139], v149 offset:40960
	s_waitcnt lgkmcnt(7)
	v_mfma_f32_16x16x32_bf16 v[44:47], v[140:143], v[52:55], v[44:47]
	ds_read_b128 v[140:143], v149 offset:45056
	s_waitcnt lgkmcnt(7)
	v_mfma_f32_16x16x32_bf16 v[32:35], v[112:115], v[56:59], v[32:35]
	s_waitcnt lgkmcnt(6)
	v_mfma_f32_16x16x32_bf16 v[36:39], v[116:119], v[56:59], v[36:39]
	s_waitcnt lgkmcnt(5)
	v_mfma_f32_16x16x32_bf16 v[40:43], v[120:123], v[56:59], v[40:43]
	s_waitcnt lgkmcnt(4)
	v_mfma_f32_16x16x32_bf16 v[44:47], v[124:127], v[56:59], v[44:47]
	s_waitcnt lgkmcnt(3)
	v_mfma_f32_16x16x32_bf16 v[32:35], v[128:131], v[60:63], v[32:35]
	s_waitcnt lgkmcnt(2)
	v_mfma_f32_16x16x32_bf16 v[36:39], v[132:135], v[60:63], v[36:39]
	s_waitcnt lgkmcnt(1)
	v_mfma_f32_16x16x32_bf16 v[40:43], v[136:139], v[60:63], v[40:43]
	s_waitcnt lgkmcnt(0)
	v_mfma_f32_16x16x32_bf16 v[44:47], v[140:143], v[60:63], v[44:47]
	ds_read_b32 v0, v184 offset:896
	ds_read_b32 v1, v185 offset:896
	ds_read_b32 v2, v186 offset:896
	ds_read_b32 v3, v187 offset:896
	ds_read_b32 v4, v188 offset:896
	ds_read_b32 v5, v189 offset:896
	ds_read_b32 v6, v190 offset:896
	ds_read_b32 v7, v191 offset:896
	ds_read_b32 v8, v192 offset:896
	ds_read_b32 v9, v193 offset:896
	ds_read_b32 v10, v194 offset:896
	ds_read_b32 v11, v195 offset:896
	ds_read_b32 v12, v196 offset:896
	ds_read_b32 v13, v197 offset:896
	ds_read_b32 v14, v198 offset:896
	ds_read_b32 v15, v199 offset:896
	ds_read_b32 v16, v184 offset:1024
	ds_read_b32 v17, v185 offset:1024
	ds_read_b32 v18, v186 offset:1024
	ds_read_b32 v19, v187 offset:1024
	ds_read_b32 v20, v188 offset:1024
	ds_read_b32 v21, v189 offset:1024
	ds_read_b32 v22, v190 offset:1024
	ds_read_b32 v23, v191 offset:1024
	ds_read_b32 v24, v192 offset:1024
	ds_read_b32 v25, v193 offset:1024
	ds_read_b32 v26, v194 offset:1024
	ds_read_b32 v27, v195 offset:1024
	ds_read_b32 v28, v196 offset:1024
	ds_read_b32 v29, v197 offset:1024
	ds_read_b32 v30, v198 offset:1024
	ds_read_b32 v31, v199 offset:1024
	s_waitcnt lgkmcnt(0)
	s_barrier
; __device__ __forceinline__ void attn_phase(const Params& P, char* smem_raw) {
;     ...
;     for (int ck = 0; ck < 6; ++ck) {
;       int lane_c = lane;
;       asm volatile("" : "+v"(lane_c));
;       __syncthreads();
; #pragma unroll
;       for (int i = 0; i < 4; ++i) {
;         const int idx = tid + 256 * i;
;         *reinterpret_cast<uint4*>(&sm_k[(idx >> 3) * LDSS + (idx & 7) * 8]) = kreg[i];
;         *reinterpret_cast<uint4*>(&sm_vt[(idx >> 4) * 136 + (idx & 15) * 8]) = vreg[i];
;       }
;       __syncthreads();
;       f32x4 sacc[8];
; #pragma unroll
;       for (int t8 = 0; t8 < 8; ++t8) sacc[t8] = f32x4{0.f, 0.f, 0.f, 0.f};
; #pragma unroll
;       for (int s = 0; s < 2; ++s)
; #pragma unroll
;         for (int t8 = 0; t8 < 8; ++t8) {
;           const bf16x8 kf = *reinterpret_cast<const bf16x8*>(&sm_k[(t8 * 16 + (lane_c & 15)) * LDSS + s * 32 + (lane_c >> 4) * 8]);
;           sacc[t8] = __builtin_amdgcn_mfma_f32_16x16x32_bf16(qf[s], kf, sacc[t8], 0, 0, 0);
;         }
;       if (ck < 5) {
;         ATT_ISSUE(t, ck + 1)
;       } else if (t + VGRID < 8192) {
;         ATT_ISSUE(t + VGRID, 0)
;         ATT_QLOAD(t + VGRID)
;       }
;       if (ck < 4) {
;         const float* rb0 = sm_rpb + (rs + ck * 2 - r + 7) * 31;
; #pragma unroll
;         for (int t8 = 0; t8 < 8; ++t8)
; #pragma unroll
;           for (int reg = 0; reg < 4; ++reg)
;             sacc[t8][reg] += rb0[(t8 >> 2) * 31 + dco[reg][t8 & 3]];
;       }
; #pragma unroll
;       for (int reg = 0; reg < 4; ++reg) {
;         float mx = sacc[0][reg];
; #pragma unroll
;         for (int t8 = 1; t8 < 8; ++t8) mx = fmaxf(mx, sacc[t8][reg]);
;         mx = row16_max(mx);
;         const float mnew = fmaxf(mrow[reg], mx);
;         const float alpha = __builtin_amdgcn_exp2f(mrow[reg] - mnew);
;         mrow[reg] = mnew;
;         float rsum = 0.f;
; #pragma unroll
;         for (int t8 = 0; t8 < 8; ++t8) {
;           const float p = __builtin_amdgcn_exp2f(sacc[t8][reg] - mnew);
;           rsum += p;
;           sm_p[(wid * 16 + (lane_c >> 4) * 4 + reg) * 136 + t8 * 16 + (lane_c & 15)] = f2bf(p);
;         }
;         rsum = row16_sum(rsum);
;         lrow[reg] = lrow[reg] * alpha + rsum;
; #pragma unroll
;         for (int td = 0; td < 4; ++td) o[td][reg] *= alpha;
;       }
	ds_read_b128 v[112:115], v144 offset:0
	ds_read_b128 v[116:119], v145 offset:0
	ds_read_b128 v[120:123], v144 offset:512
	ds_read_b128 v[124:127], v145 offset:512
	ds_read_b128 v[128:131], v144 offset:4096
	ds_read_b128 v[132:135], v145 offset:4096
	ds_read_b128 v[136:139], v144 offset:4608
	ds_read_b128 v[140:143], v145 offset:4608
	s_waitcnt lgkmcnt(7)
	v_mfma_f32_16x16x32_bf16 v[0:3], v[112:115], v[64:67], v[0:3]
	ds_read_b128 v[112:115], v144 offset:8192
	s_waitcnt lgkmcnt(7)
	v_mfma_f32_16x16x32_bf16 v[0:3], v[116:119], v[68:71], v[0:3]
	ds_read_b128 v[116:119], v145 offset:8192
	s_waitcnt lgkmcnt(7)
	v_mfma_f32_16x16x32_bf16 v[4:7], v[120:123], v[64:67], v[4:7]
	ds_read_b128 v[120:123], v144 offset:8704
	s_waitcnt lgkmcnt(7)
	v_mfma_f32_16x16x32_bf16 v[4:7], v[124:127], v[68:71], v[4:7]
	ds_read_b128 v[124:127], v145 offset:8704
	s_waitcnt lgkmcnt(7)
	v_mfma_f32_16x16x32_bf16 v[8:11], v[128:131], v[64:67], v[8:11]
	ds_read_b128 v[128:131], v144 offset:12288
	s_waitcnt lgkmcnt(7)
	v_mfma_f32_16x16x32_bf16 v[8:11], v[132:135], v[68:71], v[8:11]
	ds_read_b128 v[132:135], v145 offset:12288
	s_waitcnt lgkmcnt(7)
	v_mfma_f32_16x16x32_bf16 v[12:15], v[136:139], v[64:67], v[12:15]
	ds_read_b128 v[136:139], v144 offset:12800
	s_waitcnt lgkmcnt(7)
	v_mfma_f32_16x16x32_bf16 v[12:15], v[140:143], v[68:71], v[12:15]
	ds_read_b128 v[140:143], v145 offset:12800
	s_waitcnt lgkmcnt(7)
	v_mfma_f32_16x16x32_bf16 v[16:19], v[112:115], v[64:67], v[16:19]
	s_waitcnt lgkmcnt(6)
	v_mfma_f32_16x16x32_bf16 v[16:19], v[116:119], v[68:71], v[16:19]
	s_waitcnt lgkmcnt(5)
	v_mfma_f32_16x16x32_bf16 v[20:23], v[120:123], v[64:67], v[20:23]
	s_waitcnt lgkmcnt(4)
	v_mfma_f32_16x16x32_bf16 v[20:23], v[124:127], v[68:71], v[20:23]
	s_waitcnt lgkmcnt(3)
	v_mfma_f32_16x16x32_bf16 v[24:27], v[128:131], v[64:67], v[24:27]
	s_waitcnt lgkmcnt(2)
	v_mfma_f32_16x16x32_bf16 v[24:27], v[132:135], v[68:71], v[24:27]
	s_waitcnt lgkmcnt(1)
	v_mfma_f32_16x16x32_bf16 v[28:31], v[136:139], v[64:67], v[28:31]
	s_waitcnt lgkmcnt(0)
	v_mfma_f32_16x16x32_bf16 v[28:31], v[140:143], v[68:71], v[28:31]
	s_nop 7
	v_max3_f32 v203, v0, v1, v2
	v_max3_f32 v203, v203, v3, v4
	v_max3_f32 v203, v203, v5, v6
	v_max3_f32 v203, v203, v7, v8
	v_max3_f32 v203, v203, v9, v10
	v_max3_f32 v203, v203, v11, v12
	v_max3_f32 v203, v203, v13, v14
	v_max3_f32 v203, v203, v15, v16
	v_max3_f32 v203, v203, v17, v18
	v_max3_f32 v203, v203, v19, v20
	v_max3_f32 v203, v203, v21, v22
	v_max3_f32 v203, v203, v23, v24
	v_max3_f32 v203, v203, v25, v26
	v_max3_f32 v203, v203, v27, v28
	v_max3_f32 v203, v203, v29, v30
	v_max_f32_e32 v203, v203, v31
	v_mov_b32_e32 v205, v203
	s_nop 1
	v_permlane16_swap_b32_e32 v203, v205
	v_max_f32_e32 v203, v203, v205
	v_mov_b32_e32 v205, v203
	s_nop 1
	v_permlane32_swap_b32_e32 v203, v205
	v_max_f32_e32 v203, v203, v205
	v_max_f32_e32 v218, v200, v203
	v_sub_f32_e32 v220, v200, v218
	v_mov_b32_e32 v219, v218
	v_exp_f32_e32 v220, v220
	v_mov_b32_e32 v200, v218
	v_pk_add_f32 v[0:1], v[0:1], v[218:219] neg_lo:[0,1] neg_hi:[0,1]
	v_pk_add_f32 v[2:3], v[2:3], v[218:219] neg_lo:[0,1] neg_hi:[0,1]
	v_pk_add_f32 v[4:5], v[4:5], v[218:219] neg_lo:[0,1] neg_hi:[0,1]
	v_pk_add_f32 v[6:7], v[6:7], v[218:219] neg_lo:[0,1] neg_hi:[0,1]
	v_pk_add_f32 v[8:9], v[8:9], v[218:219] neg_lo:[0,1] neg_hi:[0,1]
	v_pk_add_f32 v[10:11], v[10:11], v[218:219] neg_lo:[0,1] neg_hi:[0,1]
	v_pk_add_f32 v[12:13], v[12:13], v[218:219] neg_lo:[0,1] neg_hi:[0,1]
	v_pk_add_f32 v[14:15], v[14:15], v[218:219] neg_lo:[0,1] neg_hi:[0,1]
	v_pk_add_f32 v[16:17], v[16:17], v[218:219] neg_lo:[0,1] neg_hi:[0,1]
	v_pk_add_f32 v[18:19], v[18:19], v[218:219] neg_lo:[0,1] neg_hi:[0,1]
	v_pk_add_f32 v[20:21], v[20:21], v[218:219] neg_lo:[0,1] neg_hi:[0,1]
	v_pk_add_f32 v[22:23], v[22:23], v[218:219] neg_lo:[0,1] neg_hi:[0,1]
	v_pk_add_f32 v[24:25], v[24:25], v[218:219] neg_lo:[0,1] neg_hi:[0,1]
	v_pk_add_f32 v[26:27], v[26:27], v[218:219] neg_lo:[0,1] neg_hi:[0,1]
	v_pk_add_f32 v[28:29], v[28:29], v[218:219] neg_lo:[0,1] neg_hi:[0,1]
	v_pk_add_f32 v[30:31], v[30:31], v[218:219] neg_lo:[0,1] neg_hi:[0,1]
	v_exp_f32_e32 v0, v0
	s_waitcnt vmcnt(0)
	v_exp_f32_e32 v1, v1
	ds_write_b128 v150, v[80:83] offset:32768
	v_exp_f32_e32 v2, v2
	ds_write_b128 v150, v[84:87] offset:36864
	v_exp_f32_e32 v3, v3
	ds_write_b128 v150, v[88:91] offset:40960
	v_exp_f32_e32 v4, v4
	ds_write_b128 v150, v[92:95] offset:45056
	v_exp_f32_e32 v5, v5
	ds_write_b128 v151, v[96:99] offset:32768
	v_exp_f32_e32 v6, v6
	ds_write_b128 v151, v[100:103] offset:36864
	v_exp_f32_e32 v7, v7
	ds_write_b128 v151, v[104:107] offset:40960
	v_exp_f32_e32 v8, v8
	ds_write_b128 v151, v[108:111] offset:45056
	v_exp_f32_e32 v9, v9
	s_add_u32 s100, s16, 0x0
	v_exp_f32_e32 v10, v10
	s_addc_u32 s101, s17, 0
	v_exp_f32_e32 v11, v11
	s_add_u32 s0, s36, 0x0
	v_exp_f32_e32 v12, v12
	s_addc_u32 s1, s37, 0
	v_exp_f32_e32 v13, v13
	global_load_dwordx4 v[80:83], v154, s[100:101] offset:2048
	v_exp_f32_e32 v14, v14
	global_load_dwordx4 v[96:99], v162, s[0:1]
	v_exp_f32_e32 v15, v15
	global_load_dwordx4 v[84:87], v155, s[100:101] offset:2048
	v_exp_f32_e32 v16, v16
	global_load_dwordx4 v[100:103], v163, s[0:1]
	v_exp_f32_e32 v17, v17
	global_load_dwordx4 v[88:91], v156, s[100:101] offset:2048
	v_exp_f32_e32 v18, v18
	global_load_dwordx4 v[104:107], v164, s[0:1]
	v_exp_f32_e32 v19, v19
	global_load_dwordx4 v[92:95], v157, s[100:101] offset:2048
	v_exp_f32_e32 v20, v20
	global_load_dwordx4 v[108:111], v165, s[0:1]
	v_exp_f32_e32 v21, v21
	v_exp_f32_e32 v22, v22
	v_exp_f32_e32 v23, v23
	v_exp_f32_e32 v24, v24
	v_exp_f32_e32 v25, v25
	v_exp_f32_e32 v26, v26
	v_exp_f32_e32 v27, v27
	v_exp_f32_e32 v28, v28
; __device__ __forceinline__ void attn_phase(const Params& P, char* smem_raw) {
;     ...
;       if (ck < 4) {
;         const float* rb0 = sm_rpb + (rs + ck * 2 - r + 7) * 31;
; #pragma unroll
;         for (int t8 = 0; t8 < 8; ++t8)
; #pragma unroll
;           for (int reg = 0; reg < 4; ++reg)
;             sacc[t8][reg] += rb0[(t8 >> 2) * 31 + dco[reg][t8 & 3]];
;       }
; #pragma unroll
;       for (int reg = 0; reg < 4; ++reg) {
;         float mx = sacc[0][reg];
; #pragma unroll
;         for (int t8 = 1; t8 < 8; ++t8) mx = fmaxf(mx, sacc[t8][reg]);
;         mx = row16_max(mx);
;         const float mnew = fmaxf(mrow[reg], mx);
;         const float alpha = __builtin_amdgcn_exp2f(mrow[reg] - mnew);
;         mrow[reg] = mnew;
;         float rsum = 0.f;
; #pragma unroll
;         for (int t8 = 0; t8 < 8; ++t8) {
;           const float p = __builtin_amdgcn_exp2f(sacc[t8][reg] - mnew);
;           rsum += p;
;           sm_p[(wid * 16 + (lane_c >> 4) * 4 + reg) * 136 + t8 * 16 + (lane_c & 15)] = f2bf(p);
;         }
;         rsum = row16_sum(rsum);
;         lrow[reg] = lrow[reg] * alpha + rsum;
; #pragma unroll
;         for (int td = 0; td < 4; ++td) o[td][reg] *= alpha;
;       }
;       asm volatile("s_waitcnt lgkmcnt(0)" ::: "memory");
; #pragma unroll
;       for (int s4 = 0; s4 < 4; ++s4) {
;         const bf16x8 pf = *reinterpret_cast<const bf16x8*>(&sm_p[(wid * 16 + (lane_c & 15)) * 136 + s4 * 32 + (lane_c >> 4) * 8]);
; #pragma unroll
;         for (int td = 0; td < 4; ++td) {
;           const bf16x8 vf = *reinterpret_cast<const bf16x8*>(&sm_vt[(td * 16 + (lane_c & 15)) * 136 + s4 * 32 + (lane_c >> 4) * 8]);
;           o[td] = __builtin_amdgcn_mfma_f32_16x16x32_bf16(pf, vf, o[td], 0, 0, 0);
;         }
;       }
	v_exp_f32_e32 v29, v29
	v_exp_f32_e32 v30, v30
	v_exp_f32_e32 v31, v31
	ds_read_b128 v[112:115], v146 offset:0
	ds_read_b128 v[116:119], v146 offset:4096
	ds_read_b128 v[120:123], v146 offset:8192
	ds_read_b128 v[124:127], v146 offset:12288
	ds_read_b128 v[128:131], v147 offset:0
	ds_read_b128 v[132:135], v147 offset:4096
	ds_read_b128 v[136:139], v147 offset:8192
	ds_read_b128 v[140:143], v147 offset:12288
	v_mov_b32_e32 v221, v220
	v_pk_add_f32 v[222:223], v[0:1], v[2:3]
	v_pk_add_f32 v[222:223], v[222:223], v[4:5]
	v_pk_add_f32 v[222:223], v[222:223], v[6:7]
	v_pk_add_f32 v[222:223], v[222:223], v[8:9]
	v_pk_add_f32 v[222:223], v[222:223], v[10:11]
	v_pk_add_f32 v[222:223], v[222:223], v[12:13]
	v_pk_add_f32 v[222:223], v[222:223], v[14:15]
	v_pk_add_f32 v[222:223], v[222:223], v[16:17]
	v_pk_add_f32 v[222:223], v[222:223], v[18:19]
	v_pk_add_f32 v[222:223], v[222:223], v[20:21]
	v_pk_add_f32 v[222:223], v[222:223], v[22:23]
	v_pk_add_f32 v[222:223], v[222:223], v[24:25]
	v_pk_add_f32 v[222:223], v[222:223], v[26:27]
	v_pk_add_f32 v[222:223], v[222:223], v[28:29]
	v_pk_add_f32 v[222:223], v[222:223], v[30:31]
	v_pk_mul_f32 v[32:33], v[32:33], v[220:221]
	v_pk_mul_f32 v[34:35], v[34:35], v[220:221]
	v_pk_mul_f32 v[36:37], v[36:37], v[220:221]
	v_pk_mul_f32 v[38:39], v[38:39], v[220:221]
	v_pk_mul_f32 v[40:41], v[40:41], v[220:221]
	v_pk_mul_f32 v[42:43], v[42:43], v[220:221]
	v_pk_mul_f32 v[44:45], v[44:45], v[220:221]
	v_pk_mul_f32 v[46:47], v[46:47], v[220:221]
	v_add_f32_e32 v203, v222, v223
	v_fma_f32 v201, v201, v220, v203
	v_cvt_pk_bf16_f32 v48, v0, v1
	v_cvt_pk_bf16_f32 v49, v2, v3
	v_cvt_pk_bf16_f32 v50, v4, v5
	v_cvt_pk_bf16_f32 v51, v6, v7
	v_cvt_pk_bf16_f32 v52, v8, v9
	v_cvt_pk_bf16_f32 v53, v10, v11
	v_cvt_pk_bf16_f32 v54, v12, v13
	v_cvt_pk_bf16_f32 v55, v14, v15
	v_cvt_pk_bf16_f32 v56, v16, v17
	v_cvt_pk_bf16_f32 v57, v18, v19
	v_cvt_pk_bf16_f32 v58, v20, v21
	v_cvt_pk_bf16_f32 v59, v22, v23
	v_cvt_pk_bf16_f32 v60, v24, v25
	v_cvt_pk_bf16_f32 v61, v26, v27
	v_cvt_pk_bf16_f32 v62, v28, v29
	v_cvt_pk_bf16_f32 v63, v30, v31
	s_waitcnt lgkmcnt(7)
	v_mfma_f32_16x16x32_bf16 v[32:35], v[112:115], v[48:51], v[32:35]
	ds_read_b128 v[112:115], v148 offset:0
	s_waitcnt lgkmcnt(7)
	v_mfma_f32_16x16x32_bf16 v[36:39], v[116:119], v[48:51], v[36:39]
	ds_read_b128 v[116:119], v148 offset:4096
	s_waitcnt lgkmcnt(7)
	v_mfma_f32_16x16x32_bf16 v[40:43], v[120:123], v[48:51], v[40:43]
	ds_read_b128 v[120:123], v148 offset:8192
	s_waitcnt lgkmcnt(7)
	v_mfma_f32_16x16x32_bf16 v[44:47], v[124:127], v[48:51], v[44:47]
	ds_read_b128 v[124:127], v148 offset:12288
	s_waitcnt lgkmcnt(7)
	v_mfma_f32_16x16x32_bf16 v[32:35], v[128:131], v[52:55], v[32:35]
	ds_read_b128 v[128:131], v149 offset:0
	s_waitcnt lgkmcnt(7)
	v_mfma_f32_16x16x32_bf16 v[36:39], v[132:135], v[52:55], v[36:39]
	ds_read_b128 v[132:135], v149 offset:4096
	s_waitcnt lgkmcnt(7)
	v_mfma_f32_16x16x32_bf16 v[40:43], v[136:139], v[52:55], v[40:43]
	ds_read_b128 v[136:139], v149 offset:8192
	s_waitcnt lgkmcnt(7)
	v_mfma_f32_16x16x32_bf16 v[44:47], v[140:143], v[52:55], v[44:47]
	ds_read_b128 v[140:143], v149 offset:12288
	s_waitcnt lgkmcnt(7)
	v_mfma_f32_16x16x32_bf16 v[32:35], v[112:115], v[56:59], v[32:35]
	s_waitcnt lgkmcnt(6)
	v_mfma_f32_16x16x32_bf16 v[36:39], v[116:119], v[56:59], v[36:39]
	s_waitcnt lgkmcnt(5)
	v_mfma_f32_16x16x32_bf16 v[40:43], v[120:123], v[56:59], v[40:43]
	s_waitcnt lgkmcnt(4)
	v_mfma_f32_16x16x32_bf16 v[44:47], v[124:127], v[56:59], v[44:47]
	s_waitcnt lgkmcnt(3)
	v_mfma_f32_16x16x32_bf16 v[32:35], v[128:131], v[60:63], v[32:35]
	s_waitcnt lgkmcnt(2)
	v_mfma_f32_16x16x32_bf16 v[36:39], v[132:135], v[60:63], v[36:39]
	s_waitcnt lgkmcnt(1)
	v_mfma_f32_16x16x32_bf16 v[40:43], v[136:139], v[60:63], v[40:43]
	s_waitcnt lgkmcnt(0)
	v_mfma_f32_16x16x32_bf16 v[44:47], v[140:143], v[60:63], v[44:47]
	ds_read_b32 v0, v184 offset:1152
	ds_read_b32 v1, v185 offset:1152
	ds_read_b32 v2, v186 offset:1152
	ds_read_b32 v3, v187 offset:1152
	ds_read_b32 v4, v188 offset:1152
	ds_read_b32 v5, v189 offset:1152
	ds_read_b32 v6, v190 offset:1152
	ds_read_b32 v7, v191 offset:1152
	ds_read_b32 v8, v192 offset:1152
	ds_read_b32 v9, v193 offset:1152
	ds_read_b32 v10, v194 offset:1152
	ds_read_b32 v11, v195 offset:1152
	ds_read_b32 v12, v196 offset:1152
	ds_read_b32 v13, v197 offset:1152
	ds_read_b32 v14, v198 offset:1152
	ds_read_b32 v15, v199 offset:1152
	ds_read_b32 v16, v184 offset:1280
	ds_read_b32 v17, v185 offset:1280
	ds_read_b32 v18, v186 offset:1280
	ds_read_b32 v19, v187 offset:1280
	ds_read_b32 v20, v188 offset:1280
	ds_read_b32 v21, v189 offset:1280
	ds_read_b32 v22, v190 offset:1280
	ds_read_b32 v23, v191 offset:1280
	ds_read_b32 v24, v192 offset:1280
	ds_read_b32 v25, v193 offset:1280
	ds_read_b32 v26, v194 offset:1280
	ds_read_b32 v27, v195 offset:1280
	ds_read_b32 v28, v196 offset:1280
	ds_read_b32 v29, v197 offset:1280
	ds_read_b32 v30, v198 offset:1280
	ds_read_b32 v31, v199 offset:1280
	s_waitcnt lgkmcnt(0)
	s_barrier
; __device__ __forceinline__ void attn_phase(const Params& P, char* smem_raw) {
;     ...
;     for (int ck = 0; ck < 6; ++ck) {
;       int lane_c = lane;
;       asm volatile("" : "+v"(lane_c));
;       __syncthreads();
; #pragma unroll
;       for (int i = 0; i < 4; ++i) {
;         const int idx = tid + 256 * i;
;         *reinterpret_cast<uint4*>(&sm_k[(idx >> 3) * LDSS + (idx & 7) * 8]) = kreg[i];
;         *reinterpret_cast<uint4*>(&sm_vt[(idx >> 4) * 136 + (idx & 15) * 8]) = vreg[i];
;       }
;       __syncthreads();
;       f32x4 sacc[8];
; #pragma unroll
;       for (int t8 = 0; t8 < 8; ++t8) sacc[t8] = f32x4{0.f, 0.f, 0.f, 0.f};
; #pragma unroll
;       for (int s = 0; s < 2; ++s)
; #pragma unroll
;         for (int t8 = 0; t8 < 8; ++t8) {
;           const bf16x8 kf = *reinterpret_cast<const bf16x8*>(&sm_k[(t8 * 16 + (lane_c & 15)) * LDSS + s * 32 + (lane_c >> 4) * 8]);
;           sacc[t8] = __builtin_amdgcn_mfma_f32_16x16x32_bf16(qf[s], kf, sacc[t8], 0, 0, 0);
;         }
;       if (ck < 5) {
;         ATT_ISSUE(t, ck + 1)
;       } else if (t + VGRID < 8192) {
;         ATT_ISSUE(t + VGRID, 0)
;         ATT_QLOAD(t + VGRID)
;       }
;       if (ck < 4) {
;         const float* rb0 = sm_rpb + (rs + ck * 2 - r + 7) * 31;
; #pragma unroll
;         for (int t8 = 0; t8 < 8; ++t8)
; #pragma unroll
;           for (int reg = 0; reg < 4; ++reg)
;             sacc[t8][reg] += rb0[(t8 >> 2) * 31 + dco[reg][t8 & 3]];
;       }
; #pragma unroll
;       for (int reg = 0; reg < 4; ++reg) {
;         float mx = sacc[0][reg];
; #pragma unroll
;         for (int t8 = 1; t8 < 8; ++t8) mx = fmaxf(mx, sacc[t8][reg]);
;         mx = row16_max(mx);
;         const float mnew = fmaxf(mrow[reg], mx);
;         const float alpha = __builtin_amdgcn_exp2f(mrow[reg] - mnew);
;         mrow[reg] = mnew;
;         float rsum = 0.f;
; #pragma unroll
;         for (int t8 = 0; t8 < 8; ++t8) {
;           const float p = __builtin_amdgcn_exp2f(sacc[t8][reg] - mnew);
;           rsum += p;
;           sm_p[(wid * 16 + (lane_c >> 4) * 4 + reg) * 136 + t8 * 16 + (lane_c & 15)] = f2bf(p);
;         }
;         rsum = row16_sum(rsum);
;         lrow[reg] = lrow[reg] * alpha + rsum;
; #pragma unroll
;         for (int td = 0; td < 4; ++td) o[td][reg] *= alpha;
;       }
	ds_read_b128 v[112:115], v144 offset:32768
	ds_read_b128 v[116:119], v145 offset:32768
	ds_read_b128 v[120:123], v144 offset:33280
	ds_read_b128 v[124:127], v145 offset:33280
	ds_read_b128 v[128:131], v144 offset:36864
	ds_read_b128 v[132:135], v145 offset:36864
	ds_read_b128 v[136:139], v144 offset:37376
	ds_read_b128 v[140:143], v145 offset:37376
	s_waitcnt lgkmcnt(7)
	v_mfma_f32_16x16x32_bf16 v[0:3], v[112:115], v[64:67], v[0:3]
	ds_read_b128 v[112:115], v144 offset:40960
	s_waitcnt lgkmcnt(7)
	v_mfma_f32_16x16x32_bf16 v[0:3], v[116:119], v[68:71], v[0:3]
	ds_read_b128 v[116:119], v145 offset:40960
	s_waitcnt lgkmcnt(7)
	v_mfma_f32_16x16x32_bf16 v[4:7], v[120:123], v[64:67], v[4:7]
	ds_read_b128 v[120:123], v144 offset:41472
	s_waitcnt lgkmcnt(7)
	v_mfma_f32_16x16x32_bf16 v[4:7], v[124:127], v[68:71], v[4:7]
	ds_read_b128 v[124:127], v145 offset:41472
	s_waitcnt lgkmcnt(7)
	v_mfma_f32_16x16x32_bf16 v[8:11], v[128:131], v[64:67], v[8:11]
	ds_read_b128 v[128:131], v144 offset:45056
	s_waitcnt lgkmcnt(7)
	v_mfma_f32_16x16x32_bf16 v[8:11], v[132:135], v[68:71], v[8:11]
	ds_read_b128 v[132:135], v145 offset:45056
	s_waitcnt lgkmcnt(7)
	v_mfma_f32_16x16x32_bf16 v[12:15], v[136:139], v[64:67], v[12:15]
	ds_read_b128 v[136:139], v144 offset:45568
	s_waitcnt lgkmcnt(7)
	v_mfma_f32_16x16x32_bf16 v[12:15], v[140:143], v[68:71], v[12:15]
	ds_read_b128 v[140:143], v145 offset:45568
	s_waitcnt lgkmcnt(7)
	v_mfma_f32_16x16x32_bf16 v[16:19], v[112:115], v[64:67], v[16:19]
	s_waitcnt lgkmcnt(6)
	v_mfma_f32_16x16x32_bf16 v[16:19], v[116:119], v[68:71], v[16:19]
	s_waitcnt lgkmcnt(5)
	v_mfma_f32_16x16x32_bf16 v[20:23], v[120:123], v[64:67], v[20:23]
	s_waitcnt lgkmcnt(4)
	v_mfma_f32_16x16x32_bf16 v[20:23], v[124:127], v[68:71], v[20:23]
	s_waitcnt lgkmcnt(3)
	v_mfma_f32_16x16x32_bf16 v[24:27], v[128:131], v[64:67], v[24:27]
	s_waitcnt lgkmcnt(2)
	v_mfma_f32_16x16x32_bf16 v[24:27], v[132:135], v[68:71], v[24:27]
	s_waitcnt lgkmcnt(1)
	v_mfma_f32_16x16x32_bf16 v[28:31], v[136:139], v[64:67], v[28:31]
	s_waitcnt lgkmcnt(0)
	v_mfma_f32_16x16x32_bf16 v[28:31], v[140:143], v[68:71], v[28:31]
	s_nop 7
	v_max3_f32 v203, v0, v1, v2
	v_max3_f32 v203, v203, v3, v4
	v_max3_f32 v203, v203, v5, v6
	v_max3_f32 v203, v203, v7, v8
	v_max3_f32 v203, v203, v9, v10
	v_max3_f32 v203, v203, v11, v12
	v_max3_f32 v203, v203, v13, v14
	v_max3_f32 v203, v203, v15, v16
	v_max3_f32 v203, v203, v17, v18
	v_max3_f32 v203, v203, v19, v20
	v_max3_f32 v203, v203, v21, v22
	v_max3_f32 v203, v203, v23, v24
	v_max3_f32 v203, v203, v25, v26
	v_max3_f32 v203, v203, v27, v28
	v_max3_f32 v203, v203, v29, v30
	v_max_f32_e32 v203, v203, v31
	v_mov_b32_e32 v205, v203
	s_nop 1
	v_permlane16_swap_b32_e32 v203, v205
	v_max_f32_e32 v203, v203, v205
	v_mov_b32_e32 v205, v203
	s_nop 1
	v_permlane32_swap_b32_e32 v203, v205
	v_max_f32_e32 v203, v203, v205
	v_max_f32_e32 v218, v200, v203
	v_sub_f32_e32 v220, v200, v218
	v_mov_b32_e32 v219, v218
	v_exp_f32_e32 v220, v220
	v_mov_b32_e32 v200, v218
	v_pk_add_f32 v[0:1], v[0:1], v[218:219] neg_lo:[0,1] neg_hi:[0,1]
	v_pk_add_f32 v[2:3], v[2:3], v[218:219] neg_lo:[0,1] neg_hi:[0,1]
	v_pk_add_f32 v[4:5], v[4:5], v[218:219] neg_lo:[0,1] neg_hi:[0,1]
	v_pk_add_f32 v[6:7], v[6:7], v[218:219] neg_lo:[0,1] neg_hi:[0,1]
	v_pk_add_f32 v[8:9], v[8:9], v[218:219] neg_lo:[0,1] neg_hi:[0,1]
	v_pk_add_f32 v[10:11], v[10:11], v[218:219] neg_lo:[0,1] neg_hi:[0,1]
	v_pk_add_f32 v[12:13], v[12:13], v[218:219] neg_lo:[0,1] neg_hi:[0,1]
	v_pk_add_f32 v[14:15], v[14:15], v[218:219] neg_lo:[0,1] neg_hi:[0,1]
	v_pk_add_f32 v[16:17], v[16:17], v[218:219] neg_lo:[0,1] neg_hi:[0,1]
	v_pk_add_f32 v[18:19], v[18:19], v[218:219] neg_lo:[0,1] neg_hi:[0,1]
	v_pk_add_f32 v[20:21], v[20:21], v[218:219] neg_lo:[0,1] neg_hi:[0,1]
	v_pk_add_f32 v[22:23], v[22:23], v[218:219] neg_lo:[0,1] neg_hi:[0,1]
	v_pk_add_f32 v[24:25], v[24:25], v[218:219] neg_lo:[0,1] neg_hi:[0,1]
	v_pk_add_f32 v[26:27], v[26:27], v[218:219] neg_lo:[0,1] neg_hi:[0,1]
	v_pk_add_f32 v[28:29], v[28:29], v[218:219] neg_lo:[0,1] neg_hi:[0,1]
	v_pk_add_f32 v[30:31], v[30:31], v[218:219] neg_lo:[0,1] neg_hi:[0,1]
	v_exp_f32_e32 v0, v0
	s_waitcnt vmcnt(0)
	v_exp_f32_e32 v1, v1
	ds_write_b128 v150, v[80:83] offset:0
	v_exp_f32_e32 v2, v2
	ds_write_b128 v150, v[84:87] offset:4096
	v_exp_f32_e32 v3, v3
	ds_write_b128 v150, v[88:91] offset:8192
	v_exp_f32_e32 v4, v4
	ds_write_b128 v150, v[92:95] offset:12288
	v_exp_f32_e32 v5, v5
	ds_write_b128 v151, v[96:99] offset:0
	v_exp_f32_e32 v6, v6
	ds_write_b128 v151, v[100:103] offset:4096
	v_exp_f32_e32 v7, v7
	ds_write_b128 v151, v[104:107] offset:8192
	v_exp_f32_e32 v8, v8
	ds_write_b128 v151, v[108:111] offset:12288
	v_exp_f32_e32 v9, v9
	s_add_u32 s100, s16, 0xc0000
	v_exp_f32_e32 v10, v10
	s_addc_u32 s101, s17, 0
	v_exp_f32_e32 v11, v11
	s_add_u32 s0, s36, 0x100
	v_exp_f32_e32 v12, v12
	s_addc_u32 s1, s37, 0
	v_exp_f32_e32 v13, v13
	global_load_dwordx4 v[80:83], v154, s[100:101] offset:2048
	v_exp_f32_e32 v14, v14
	global_load_dwordx4 v[96:99], v162, s[0:1]
	v_exp_f32_e32 v15, v15
	global_load_dwordx4 v[84:87], v155, s[100:101] offset:2048
	v_exp_f32_e32 v16, v16
	global_load_dwordx4 v[100:103], v163, s[0:1]
	v_exp_f32_e32 v17, v17
	global_load_dwordx4 v[88:91], v156, s[100:101] offset:2048
	v_exp_f32_e32 v18, v18
	global_load_dwordx4 v[104:107], v164, s[0:1]
	v_exp_f32_e32 v19, v19
	global_load_dwordx4 v[92:95], v157, s[100:101] offset:2048
	v_exp_f32_e32 v20, v20
	global_load_dwordx4 v[108:111], v165, s[0:1]
	v_exp_f32_e32 v21, v21
	v_exp_f32_e32 v22, v22
	v_exp_f32_e32 v23, v23
	v_exp_f32_e32 v24, v24
	v_exp_f32_e32 v25, v25
	v_exp_f32_e32 v26, v26
	v_exp_f32_e32 v27, v27
; __device__ __forceinline__ void attn_phase(const Params& P, char* smem_raw) {
;     ...
; #pragma unroll
;       for (int reg = 0; reg < 4; ++reg) {
;         float mx = sacc[0][reg];
; #pragma unroll
;         for (int t8 = 1; t8 < 8; ++t8) mx = fmaxf(mx, sacc[t8][reg]);
;         mx = row16_max(mx);
;         const float mnew = fmaxf(mrow[reg], mx);
;         const float alpha = __builtin_amdgcn_exp2f(mrow[reg] - mnew);
;         mrow[reg] = mnew;
;         float rsum = 0.f;
; #pragma unroll
;         for (int t8 = 0; t8 < 8; ++t8) {
;           const float p = __builtin_amdgcn_exp2f(sacc[t8][reg] - mnew);
;           rsum += p;
;           sm_p[(wid * 16 + (lane_c >> 4) * 4 + reg) * 136 + t8 * 16 + (lane_c & 15)] = f2bf(p);
;         }
;         rsum = row16_sum(rsum);
;         lrow[reg] = lrow[reg] * alpha + rsum;
; #pragma unroll
;         for (int td = 0; td < 4; ++td) o[td][reg] *= alpha;
;       }
;       asm volatile("s_waitcnt lgkmcnt(0)" ::: "memory");
; #pragma unroll
;       for (int s4 = 0; s4 < 4; ++s4) {
;         const bf16x8 pf = *reinterpret_cast<const bf16x8*>(&sm_p[(wid * 16 + (lane_c & 15)) * 136 + s4 * 32 + (lane_c >> 4) * 8]);
; #pragma unroll
;         for (int td = 0; td < 4; ++td) {
;           const bf16x8 vf = *reinterpret_cast<const bf16x8*>(&sm_vt[(td * 16 + (lane_c & 15)) * 136 + s4 * 32 + (lane_c >> 4) * 8]);
;           o[td] = __builtin_amdgcn_mfma_f32_16x16x32_bf16(pf, vf, o[td], 0, 0, 0);
;         }
;       }
	v_exp_f32_e32 v28, v28
	v_exp_f32_e32 v29, v29
	v_exp_f32_e32 v30, v30
	v_exp_f32_e32 v31, v31
	s_and_b32 s0, s3, 0xff
	s_add_u32 s0, s0, 1
	s_min_u32 s0, s0, 15
	s_lshr_b32 s1, s0, 2
	s_and_b32 s0, s0, 3
	s_lshl_b32 s0, s0, 5
	s_lshr_b32 vcc_lo, s3, 12
	s_add_u32 s0, s0, vcc_lo
	s_sub_i32 vcc_lo, s0, 4
	s_max_i32 vcc_lo, vcc_lo, 0
	s_min_i32 vcc_lo, vcc_lo, 0x78
	s_lshl_b32 vcc_hi, s1, 13
	s_lshl_b32 m0, vcc_lo, 6
	s_add_u32 m0, m0, vcc_hi
	s_mul_i32 m0, m0, 0x1800
	s_add_u32 s12, s4, m0
	s_addc_u32 s13, s5, 0
	s_lshl_b32 m0, s1, 24
	s_lshl_b32 s100, vcc_lo, 7
	s_add_u32 m0, m0, s100
	s_add_u32 s14, s6, m0
	s_addc_u32 s15, s7, 0
	s_lshl_b32 m0, s0, 6
	s_add_u32 m0, m0, vcc_hi
	s_mul_i32 m0, m0, 0x1800
	s_add_u32 s100, s4, m0
	s_addc_u32 s101, s5, 0
	global_load_dwordx4 v[72:75], v166, s[100:101]
	global_load_dwordx4 v[76:79], v166, s[100:101] offset:64
	ds_read_b128 v[112:115], v146 offset:32768
	ds_read_b128 v[116:119], v146 offset:36864
	ds_read_b128 v[120:123], v146 offset:40960
	ds_read_b128 v[124:127], v146 offset:45056
	ds_read_b128 v[128:131], v147 offset:32768
	ds_read_b128 v[132:135], v147 offset:36864
	ds_read_b128 v[136:139], v147 offset:40960
	ds_read_b128 v[140:143], v147 offset:45056
	v_mov_b32_e32 v221, v220
	v_pk_add_f32 v[222:223], v[0:1], v[2:3]
	v_pk_add_f32 v[222:223], v[222:223], v[4:5]
	v_pk_add_f32 v[222:223], v[222:223], v[6:7]
	v_pk_add_f32 v[222:223], v[222:223], v[8:9]
	v_pk_add_f32 v[222:223], v[222:223], v[10:11]
	v_pk_add_f32 v[222:223], v[222:223], v[12:13]
	v_pk_add_f32 v[222:223], v[222:223], v[14:15]
	v_pk_add_f32 v[222:223], v[222:223], v[16:17]
	v_pk_add_f32 v[222:223], v[222:223], v[18:19]
	v_pk_add_f32 v[222:223], v[222:223], v[20:21]
	v_pk_add_f32 v[222:223], v[222:223], v[22:23]
	v_pk_add_f32 v[222:223], v[222:223], v[24:25]
	v_pk_add_f32 v[222:223], v[222:223], v[26:27]
	v_pk_add_f32 v[222:223], v[222:223], v[28:29]
	v_pk_add_f32 v[222:223], v[222:223], v[30:31]
	v_pk_mul_f32 v[32:33], v[32:33], v[220:221]
	v_pk_mul_f32 v[34:35], v[34:35], v[220:221]
	v_pk_mul_f32 v[36:37], v[36:37], v[220:221]
	v_pk_mul_f32 v[38:39], v[38:39], v[220:221]
	v_pk_mul_f32 v[40:41], v[40:41], v[220:221]
	v_pk_mul_f32 v[42:43], v[42:43], v[220:221]
	v_pk_mul_f32 v[44:45], v[44:45], v[220:221]
	v_pk_mul_f32 v[46:47], v[46:47], v[220:221]
	v_add_f32_e32 v203, v222, v223
	v_fma_f32 v201, v201, v220, v203
	v_cvt_pk_bf16_f32 v48, v0, v1
	v_cvt_pk_bf16_f32 v49, v2, v3
	v_cvt_pk_bf16_f32 v50, v4, v5
	v_cvt_pk_bf16_f32 v51, v6, v7
	v_cvt_pk_bf16_f32 v52, v8, v9
	v_cvt_pk_bf16_f32 v53, v10, v11
	v_cvt_pk_bf16_f32 v54, v12, v13
	v_cvt_pk_bf16_f32 v55, v14, v15
	v_cvt_pk_bf16_f32 v56, v16, v17
	v_cvt_pk_bf16_f32 v57, v18, v19
	v_cvt_pk_bf16_f32 v58, v20, v21
	v_cvt_pk_bf16_f32 v59, v22, v23
	v_cvt_pk_bf16_f32 v60, v24, v25
	v_cvt_pk_bf16_f32 v61, v26, v27
	v_cvt_pk_bf16_f32 v62, v28, v29
	v_cvt_pk_bf16_f32 v63, v30, v31
	s_waitcnt lgkmcnt(7)
	v_mfma_f32_16x16x32_bf16 v[32:35], v[112:115], v[48:51], v[32:35]
	ds_read_b128 v[112:115], v148 offset:32768
	s_waitcnt lgkmcnt(7)
	v_mfma_f32_16x16x32_bf16 v[36:39], v[116:119], v[48:51], v[36:39]
	ds_read_b128 v[116:119], v148 offset:36864
	s_waitcnt lgkmcnt(7)
	v_mfma_f32_16x16x32_bf16 v[40:43], v[120:123], v[48:51], v[40:43]
	ds_read_b128 v[120:123], v148 offset:40960
	s_waitcnt lgkmcnt(7)
	v_mfma_f32_16x16x32_bf16 v[44:47], v[124:127], v[48:51], v[44:47]
	ds_read_b128 v[124:127], v148 offset:45056
	s_waitcnt lgkmcnt(7)
	v_mfma_f32_16x16x32_bf16 v[32:35], v[128:131], v[52:55], v[32:35]
	ds_read_b128 v[128:131], v149 offset:32768
	s_waitcnt lgkmcnt(7)
	v_mfma_f32_16x16x32_bf16 v[36:39], v[132:135], v[52:55], v[36:39]
	ds_read_b128 v[132:135], v149 offset:36864
	s_waitcnt lgkmcnt(7)
	v_mfma_f32_16x16x32_bf16 v[40:43], v[136:139], v[52:55], v[40:43]
	ds_read_b128 v[136:139], v149 offset:40960
	s_waitcnt lgkmcnt(7)
	v_mfma_f32_16x16x32_bf16 v[44:47], v[140:143], v[52:55], v[44:47]
	ds_read_b128 v[140:143], v149 offset:45056
	s_waitcnt lgkmcnt(7)
	v_mfma_f32_16x16x32_bf16 v[32:35], v[112:115], v[56:59], v[32:35]
	s_waitcnt lgkmcnt(6)
	v_mfma_f32_16x16x32_bf16 v[36:39], v[116:119], v[56:59], v[36:39]
	s_waitcnt lgkmcnt(5)
	v_mfma_f32_16x16x32_bf16 v[40:43], v[120:123], v[56:59], v[40:43]
	s_waitcnt lgkmcnt(4)
	v_mfma_f32_16x16x32_bf16 v[44:47], v[124:127], v[56:59], v[44:47]
	s_waitcnt lgkmcnt(3)
	v_mfma_f32_16x16x32_bf16 v[32:35], v[128:131], v[60:63], v[32:35]
	s_waitcnt lgkmcnt(2)
	v_mfma_f32_16x16x32_bf16 v[36:39], v[132:135], v[60:63], v[36:39]
	s_waitcnt lgkmcnt(1)
	v_mfma_f32_16x16x32_bf16 v[40:43], v[136:139], v[60:63], v[40:43]
	s_waitcnt lgkmcnt(0)
	v_mfma_f32_16x16x32_bf16 v[44:47], v[140:143], v[60:63], v[44:47]
	s_waitcnt lgkmcnt(0)
	s_barrier
; __device__ __forceinline__ void attn_phase(const Params& P, char* smem_raw) {
;     ...
;     for (int ck = 0; ck < 6; ++ck) {
;       int lane_c = lane;
;       asm volatile("" : "+v"(lane_c));
;       __syncthreads();
; #pragma unroll
;       for (int i = 0; i < 4; ++i) {
;         const int idx = tid + 256 * i;
;         *reinterpret_cast<uint4*>(&sm_k[(idx >> 3) * LDSS + (idx & 7) * 8]) = kreg[i];
;         *reinterpret_cast<uint4*>(&sm_vt[(idx >> 4) * 136 + (idx & 15) * 8]) = vreg[i];
;       }
;       __syncthreads();
;       f32x4 sacc[8];
; #pragma unroll
;       for (int t8 = 0; t8 < 8; ++t8) sacc[t8] = f32x4{0.f, 0.f, 0.f, 0.f};
; #pragma unroll
;       for (int s = 0; s < 2; ++s)
; #pragma unroll
;         for (int t8 = 0; t8 < 8; ++t8) {
;           const bf16x8 kf = *reinterpret_cast<const bf16x8*>(&sm_k[(t8 * 16 + (lane_c & 15)) * LDSS + s * 32 + (lane_c >> 4) * 8]);
;           sacc[t8] = __builtin_amdgcn_mfma_f32_16x16x32_bf16(qf[s], kf, sacc[t8], 0, 0, 0);
;         }
;       if (ck < 5) {
;         ATT_ISSUE(t, ck + 1)
;       } else if (t + VGRID < 8192) {
;         ATT_ISSUE(t + VGRID, 0)
;         ATT_QLOAD(t + VGRID)
;       }
;       if (ck < 4) {
;         const float* rb0 = sm_rpb + (rs + ck * 2 - r + 7) * 31;
; #pragma unroll
;         for (int t8 = 0; t8 < 8; ++t8)
; #pragma unroll
;           for (int reg = 0; reg < 4; ++reg)
;             sacc[t8][reg] += rb0[(t8 >> 2) * 31 + dco[reg][t8 & 3]];
;       }
; #pragma unroll
;       for (int reg = 0; reg < 4; ++reg) {
;         float mx = sacc[0][reg];
; #pragma unroll
;         for (int t8 = 1; t8 < 8; ++t8) mx = fmaxf(mx, sacc[t8][reg]);
;         mx = row16_max(mx);
;         const float mnew = fmaxf(mrow[reg], mx);
;         const float alpha = __builtin_amdgcn_exp2f(mrow[reg] - mnew);
;         mrow[reg] = mnew;
;         float rsum = 0.f;
; #pragma unroll
;         for (int t8 = 0; t8 < 8; ++t8) {
;           const float p = __builtin_amdgcn_exp2f(sacc[t8][reg] - mnew);
;           rsum += p;
;           sm_p[(wid * 16 + (lane_c >> 4) * 4 + reg) * 136 + t8 * 16 + (lane_c & 15)] = f2bf(p);
;         }
;         rsum = row16_sum(rsum);
;         lrow[reg] = lrow[reg] * alpha + rsum;
; #pragma unroll
;         for (int td = 0; td < 4; ++td) o[td][reg] *= alpha;
;       }
	ds_read_b128 v[112:115], v144 offset:0
	ds_read_b128 v[116:119], v145 offset:0
	ds_read_b128 v[120:123], v144 offset:512
	ds_read_b128 v[124:127], v145 offset:512
	ds_read_b128 v[128:131], v144 offset:4096
	ds_read_b128 v[132:135], v145 offset:4096
	ds_read_b128 v[136:139], v144 offset:4608
	ds_read_b128 v[140:143], v145 offset:4608
	s_waitcnt lgkmcnt(7)
	v_mfma_f32_16x16x32_bf16 v[0:3], v[112:115], v[64:67], 0
	ds_read_b128 v[112:115], v144 offset:8192
	s_waitcnt lgkmcnt(7)
	v_mfma_f32_16x16x32_bf16 v[0:3], v[116:119], v[68:71], v[0:3]
	ds_read_b128 v[116:119], v145 offset:8192
	s_waitcnt lgkmcnt(7)
	v_mfma_f32_16x16x32_bf16 v[4:7], v[120:123], v[64:67], 0
	ds_read_b128 v[120:123], v144 offset:8704
	s_waitcnt lgkmcnt(7)
	v_mfma_f32_16x16x32_bf16 v[4:7], v[124:127], v[68:71], v[4:7]
	ds_read_b128 v[124:127], v145 offset:8704
	s_waitcnt lgkmcnt(7)
	v_mfma_f32_16x16x32_bf16 v[8:11], v[128:131], v[64:67], 0
	ds_read_b128 v[128:131], v144 offset:12288
	s_waitcnt lgkmcnt(7)
	v_mfma_f32_16x16x32_bf16 v[8:11], v[132:135], v[68:71], v[8:11]
	ds_read_b128 v[132:135], v145 offset:12288
	s_waitcnt lgkmcnt(7)
	v_mfma_f32_16x16x32_bf16 v[12:15], v[136:139], v[64:67], 0
	ds_read_b128 v[136:139], v144 offset:12800
	s_waitcnt lgkmcnt(7)
	v_mfma_f32_16x16x32_bf16 v[12:15], v[140:143], v[68:71], v[12:15]
	ds_read_b128 v[140:143], v145 offset:12800
	s_waitcnt lgkmcnt(7)
	v_mfma_f32_16x16x32_bf16 v[16:19], v[112:115], v[64:67], 0
	s_waitcnt lgkmcnt(6)
	v_mfma_f32_16x16x32_bf16 v[16:19], v[116:119], v[68:71], v[16:19]
	s_waitcnt lgkmcnt(5)
	v_mfma_f32_16x16x32_bf16 v[20:23], v[120:123], v[64:67], 0
	s_waitcnt lgkmcnt(4)
	v_mfma_f32_16x16x32_bf16 v[20:23], v[124:127], v[68:71], v[20:23]
	s_waitcnt lgkmcnt(3)
	v_mfma_f32_16x16x32_bf16 v[24:27], v[128:131], v[64:67], 0
	s_waitcnt lgkmcnt(2)
	v_mfma_f32_16x16x32_bf16 v[24:27], v[132:135], v[68:71], v[24:27]
	s_waitcnt lgkmcnt(1)
	v_mfma_f32_16x16x32_bf16 v[28:31], v[136:139], v[64:67], 0
	s_waitcnt lgkmcnt(0)
	v_mfma_f32_16x16x32_bf16 v[28:31], v[140:143], v[68:71], v[28:31]
	s_nop 7
	v_max3_f32 v203, v0, v1, v2
	v_max3_f32 v203, v203, v3, v4
	v_max3_f32 v203, v203, v5, v6
	v_max3_f32 v203, v203, v7, v8
	v_max3_f32 v203, v203, v9, v10
	v_max3_f32 v203, v203, v11, v12
	v_max3_f32 v203, v203, v13, v14
	v_max3_f32 v203, v203, v15, v16
	v_max3_f32 v203, v203, v17, v18
	v_max3_f32 v203, v203, v19, v20
	v_max3_f32 v203, v203, v21, v22
	v_max3_f32 v203, v203, v23, v24
	v_max3_f32 v203, v203, v25, v26
	v_max3_f32 v203, v203, v27, v28
	v_max3_f32 v203, v203, v29, v30
	v_max_f32_e32 v203, v203, v31
	v_mov_b32_e32 v205, v203
	s_nop 1
	v_permlane16_swap_b32_e32 v203, v205
	v_max_f32_e32 v203, v203, v205
	v_mov_b32_e32 v205, v203
	s_nop 1
	v_permlane32_swap_b32_e32 v203, v205
	v_max_f32_e32 v203, v203, v205
	v_max_f32_e32 v218, v200, v203
	v_sub_f32_e32 v220, v200, v218
	v_mov_b32_e32 v219, v218
	v_exp_f32_e32 v220, v220
	v_mov_b32_e32 v200, v218
	v_pk_add_f32 v[0:1], v[0:1], v[218:219] neg_lo:[0,1] neg_hi:[0,1]
	v_pk_add_f32 v[2:3], v[2:3], v[218:219] neg_lo:[0,1] neg_hi:[0,1]
	v_pk_add_f32 v[4:5], v[4:5], v[218:219] neg_lo:[0,1] neg_hi:[0,1]
	v_pk_add_f32 v[6:7], v[6:7], v[218:219] neg_lo:[0,1] neg_hi:[0,1]
	v_pk_add_f32 v[8:9], v[8:9], v[218:219] neg_lo:[0,1] neg_hi:[0,1]
	v_pk_add_f32 v[10:11], v[10:11], v[218:219] neg_lo:[0,1] neg_hi:[0,1]
	v_pk_add_f32 v[12:13], v[12:13], v[218:219] neg_lo:[0,1] neg_hi:[0,1]
	v_pk_add_f32 v[14:15], v[14:15], v[218:219] neg_lo:[0,1] neg_hi:[0,1]
	v_pk_add_f32 v[16:17], v[16:17], v[218:219] neg_lo:[0,1] neg_hi:[0,1]
	v_pk_add_f32 v[18:19], v[18:19], v[218:219] neg_lo:[0,1] neg_hi:[0,1]
	v_pk_add_f32 v[20:21], v[20:21], v[218:219] neg_lo:[0,1] neg_hi:[0,1]
	v_pk_add_f32 v[22:23], v[22:23], v[218:219] neg_lo:[0,1] neg_hi:[0,1]
	v_pk_add_f32 v[24:25], v[24:25], v[218:219] neg_lo:[0,1] neg_hi:[0,1]
	v_pk_add_f32 v[26:27], v[26:27], v[218:219] neg_lo:[0,1] neg_hi:[0,1]
	v_pk_add_f32 v[28:29], v[28:29], v[218:219] neg_lo:[0,1] neg_hi:[0,1]
	v_pk_add_f32 v[30:31], v[30:31], v[218:219] neg_lo:[0,1] neg_hi:[0,1]
	v_exp_f32_e32 v0, v0
	s_waitcnt vmcnt(2)
	v_exp_f32_e32 v1, v1
	ds_write_b128 v150, v[80:83] offset:32768
	v_exp_f32_e32 v2, v2
	ds_write_b128 v150, v[84:87] offset:36864
	v_exp_f32_e32 v3, v3
	ds_write_b128 v150, v[88:91] offset:40960
	v_exp_f32_e32 v4, v4
	ds_write_b128 v150, v[92:95] offset:45056
	v_exp_f32_e32 v5, v5
	ds_write_b128 v151, v[96:99] offset:32768
	v_exp_f32_e32 v6, v6
	ds_write_b128 v151, v[100:103] offset:36864
	v_exp_f32_e32 v7, v7
	ds_write_b128 v151, v[104:107] offset:40960
	v_exp_f32_e32 v8, v8
	ds_write_b128 v151, v[108:111] offset:45056
	v_exp_f32_e32 v9, v9
	s_add_u32 s100, s12, 0x0
	v_exp_f32_e32 v10, v10
	s_addc_u32 s101, s13, 0
	v_exp_f32_e32 v11, v11
	s_add_u32 s0, s14, 0x0
	v_exp_f32_e32 v12, v12
	s_addc_u32 s1, s15, 0
	v_exp_f32_e32 v13, v13
	global_load_dwordx4 v[80:83], v154, s[100:101] offset:2048
	v_exp_f32_e32 v14, v14
	global_load_dwordx4 v[96:99], v158, s[0:1]
	v_exp_f32_e32 v15, v15
	global_load_dwordx4 v[84:87], v155, s[100:101] offset:2048
	v_exp_f32_e32 v16, v16
	global_load_dwordx4 v[100:103], v159, s[0:1]
	v_exp_f32_e32 v17, v17
	global_load_dwordx4 v[88:91], v156, s[100:101] offset:2048
	v_exp_f32_e32 v18, v18
	global_load_dwordx4 v[104:107], v160, s[0:1]
	v_exp_f32_e32 v19, v19
	global_load_dwordx4 v[92:95], v157, s[100:101] offset:2048
	v_exp_f32_e32 v20, v20
	global_load_dwordx4 v[108:111], v161, s[0:1]
	v_exp_f32_e32 v21, v21
	v_exp_f32_e32 v22, v22
	v_exp_f32_e32 v23, v23
	v_exp_f32_e32 v24, v24
	v_exp_f32_e32 v25, v25
	v_exp_f32_e32 v26, v26
	v_exp_f32_e32 v27, v27
	v_exp_f32_e32 v28, v28
	v_exp_f32_e32 v29, v29
	v_exp_f32_e32 v30, v30
; __device__ __forceinline__ void attn_phase(const Params& P, char* smem_raw) {
;     ...
;       if (ck < 4) {
;         const float* rb0 = sm_rpb + (rs + ck * 2 - r + 7) * 31;
; #pragma unroll
;         for (int t8 = 0; t8 < 8; ++t8)
; #pragma unroll
;           for (int reg = 0; reg < 4; ++reg)
;             sacc[t8][reg] += rb0[(t8 >> 2) * 31 + dco[reg][t8 & 3]];
;     ...
; #pragma unroll
;       for (int reg = 0; reg < 4; ++reg) {
;         float mx = sacc[0][reg];
; #pragma unroll
;         for (int t8 = 1; t8 < 8; ++t8) mx = fmaxf(mx, sacc[t8][reg]);
;         mx = row16_max(mx);
;         const float mnew = fmaxf(mrow[reg], mx);
;         const float alpha = __builtin_amdgcn_exp2f(mrow[reg] - mnew);
;         mrow[reg] = mnew;
;         float rsum = 0.f;
; #pragma unroll
;         for (int t8 = 0; t8 < 8; ++t8) {
;           const float p = __builtin_amdgcn_exp2f(sacc[t8][reg] - mnew);
;           rsum += p;
;           sm_p[(wid * 16 + (lane_c >> 4) * 4 + reg) * 136 + t8 * 16 + (lane_c & 15)] = f2bf(p);
;         }
;         rsum = row16_sum(rsum);
;         lrow[reg] = lrow[reg] * alpha + rsum;
; #pragma unroll
;         for (int td = 0; td < 4; ++td) o[td][reg] *= alpha;
;       }
;       asm volatile("s_waitcnt lgkmcnt(0)" ::: "memory");
; #pragma unroll
;       for (int s4 = 0; s4 < 4; ++s4) {
;         const bf16x8 pf = *reinterpret_cast<const bf16x8*>(&sm_p[(wid * 16 + (lane_c & 15)) * 136 + s4 * 32 + (lane_c >> 4) * 8]);
; #pragma unroll
;         for (int td = 0; td < 4; ++td) {
;           const bf16x8 vf = *reinterpret_cast<const bf16x8*>(&sm_vt[(td * 16 + (lane_c & 15)) * 136 + s4 * 32 + (lane_c >> 4) * 8]);
;           o[td] = __builtin_amdgcn_mfma_f32_16x16x32_bf16(pf, vf, o[td], 0, 0, 0);
;         }
;       }
	v_exp_f32_e32 v31, v31
	s_and_b32 s0, s3, 0xff
	s_add_u32 s0, s0, 1
	s_min_u32 s0, s0, 15
	s_lshr_b32 s1, s0, 2
	s_and_b32 s0, s0, 3
	s_lshl_b32 s0, s0, 5
	s_lshr_b32 vcc_lo, s3, 12
	s_add_u32 s0, s0, vcc_lo
	s_sub_i32 vcc_lo, s0, 4
	s_max_i32 vcc_lo, vcc_lo, 0
	s_min_i32 vcc_lo, vcc_lo, 0x78
	s_lshl_b32 vcc_hi, s1, 13
	s_sub_i32 vcc_lo, vcc_lo, s0
	s_add_i32 vcc_lo, vcc_lo, 4
	s_lshl_b32 vcc_lo, vcc_lo, 7
	s_bfe_u32 m0, s3, 0x10008
	s_mul_i32 m0, m0, 0x12000
	s_add_i32 vcc_lo, vcc_lo, m0
	s_add_i32 vcc_lo, vcc_lo, 0x10010
	v_add_u32_e32 v184, vcc_lo, v168
	v_add_u32_e32 v185, vcc_lo, v169
	v_add_u32_e32 v186, vcc_lo, v170
	v_add_u32_e32 v187, vcc_lo, v171
	v_add_u32_e32 v188, vcc_lo, v172
	v_add_u32_e32 v189, vcc_lo, v173
	v_add_u32_e32 v190, vcc_lo, v174
	v_add_u32_e32 v191, vcc_lo, v175
	v_add_u32_e32 v192, vcc_lo, v176
	v_add_u32_e32 v193, vcc_lo, v177
	v_add_u32_e32 v194, vcc_lo, v178
	v_add_u32_e32 v195, vcc_lo, v179
	v_add_u32_e32 v196, vcc_lo, v180
	v_add_u32_e32 v197, vcc_lo, v181
	v_add_u32_e32 v198, vcc_lo, v182
	v_add_u32_e32 v199, vcc_lo, v183
	ds_read_b128 v[112:115], v146 offset:0
	ds_read_b128 v[116:119], v146 offset:4096
	ds_read_b128 v[120:123], v146 offset:8192
	ds_read_b128 v[124:127], v146 offset:12288
	ds_read_b128 v[128:131], v147 offset:0
	ds_read_b128 v[132:135], v147 offset:4096
	ds_read_b128 v[136:139], v147 offset:8192
	ds_read_b128 v[140:143], v147 offset:12288
	v_mov_b32_e32 v221, v220
	v_pk_add_f32 v[222:223], v[0:1], v[2:3]
	v_pk_add_f32 v[222:223], v[222:223], v[4:5]
	v_pk_add_f32 v[222:223], v[222:223], v[6:7]
	v_pk_add_f32 v[222:223], v[222:223], v[8:9]
	v_pk_add_f32 v[222:223], v[222:223], v[10:11]
	v_pk_add_f32 v[222:223], v[222:223], v[12:13]
	v_pk_add_f32 v[222:223], v[222:223], v[14:15]
	v_pk_add_f32 v[222:223], v[222:223], v[16:17]
	v_pk_add_f32 v[222:223], v[222:223], v[18:19]
	v_pk_add_f32 v[222:223], v[222:223], v[20:21]
	v_pk_add_f32 v[222:223], v[222:223], v[22:23]
	v_pk_add_f32 v[222:223], v[222:223], v[24:25]
	v_pk_add_f32 v[222:223], v[222:223], v[26:27]
	v_pk_add_f32 v[222:223], v[222:223], v[28:29]
	v_pk_add_f32 v[222:223], v[222:223], v[30:31]
	v_pk_mul_f32 v[32:33], v[32:33], v[220:221]
	v_pk_mul_f32 v[34:35], v[34:35], v[220:221]
	v_pk_mul_f32 v[36:37], v[36:37], v[220:221]
	v_pk_mul_f32 v[38:39], v[38:39], v[220:221]
	v_pk_mul_f32 v[40:41], v[40:41], v[220:221]
	v_pk_mul_f32 v[42:43], v[42:43], v[220:221]
	v_pk_mul_f32 v[44:45], v[44:45], v[220:221]
	v_pk_mul_f32 v[46:47], v[46:47], v[220:221]
	v_add_f32_e32 v203, v222, v223
	v_fma_f32 v201, v201, v220, v203
	v_cvt_pk_bf16_f32 v48, v0, v1
	v_cvt_pk_bf16_f32 v49, v2, v3
	v_cvt_pk_bf16_f32 v50, v4, v5
	v_cvt_pk_bf16_f32 v51, v6, v7
	v_cvt_pk_bf16_f32 v52, v8, v9
	v_cvt_pk_bf16_f32 v53, v10, v11
	v_cvt_pk_bf16_f32 v54, v12, v13
	v_cvt_pk_bf16_f32 v55, v14, v15
	v_cvt_pk_bf16_f32 v56, v16, v17
	v_cvt_pk_bf16_f32 v57, v18, v19
	v_cvt_pk_bf16_f32 v58, v20, v21
	v_cvt_pk_bf16_f32 v59, v22, v23
	v_cvt_pk_bf16_f32 v60, v24, v25
	v_cvt_pk_bf16_f32 v61, v26, v27
	v_cvt_pk_bf16_f32 v62, v28, v29
	v_cvt_pk_bf16_f32 v63, v30, v31
	s_waitcnt lgkmcnt(7)
	v_mfma_f32_16x16x32_bf16 v[32:35], v[112:115], v[48:51], v[32:35]
	ds_read_b128 v[112:115], v148 offset:0
	s_waitcnt lgkmcnt(7)
	v_mfma_f32_16x16x32_bf16 v[36:39], v[116:119], v[48:51], v[36:39]
	ds_read_b128 v[116:119], v148 offset:4096
	s_waitcnt lgkmcnt(7)
	v_mfma_f32_16x16x32_bf16 v[40:43], v[120:123], v[48:51], v[40:43]
	ds_read_b128 v[120:123], v148 offset:8192
	s_waitcnt lgkmcnt(7)
	v_mfma_f32_16x16x32_bf16 v[44:47], v[124:127], v[48:51], v[44:47]
	ds_read_b128 v[124:127], v148 offset:12288
	s_waitcnt lgkmcnt(7)
	v_mfma_f32_16x16x32_bf16 v[32:35], v[128:131], v[52:55], v[32:35]
	ds_read_b128 v[128:131], v149 offset:0
	s_waitcnt lgkmcnt(7)
	v_mfma_f32_16x16x32_bf16 v[36:39], v[132:135], v[52:55], v[36:39]
	ds_read_b128 v[132:135], v149 offset:4096
	s_waitcnt lgkmcnt(7)
	v_mfma_f32_16x16x32_bf16 v[40:43], v[136:139], v[52:55], v[40:43]
	ds_read_b128 v[136:139], v149 offset:8192
	s_waitcnt lgkmcnt(7)
	v_mfma_f32_16x16x32_bf16 v[44:47], v[140:143], v[52:55], v[44:47]
	ds_read_b128 v[140:143], v149 offset:12288
	s_waitcnt lgkmcnt(7)
	v_mfma_f32_16x16x32_bf16 v[32:35], v[112:115], v[56:59], v[32:35]
	s_waitcnt lgkmcnt(6)
	v_mfma_f32_16x16x32_bf16 v[36:39], v[116:119], v[56:59], v[36:39]
	s_waitcnt lgkmcnt(5)
	v_mfma_f32_16x16x32_bf16 v[40:43], v[120:123], v[56:59], v[40:43]
	s_waitcnt lgkmcnt(4)
	v_mfma_f32_16x16x32_bf16 v[44:47], v[124:127], v[56:59], v[44:47]
	s_waitcnt lgkmcnt(3)
	v_mfma_f32_16x16x32_bf16 v[32:35], v[128:131], v[60:63], v[32:35]
	s_waitcnt lgkmcnt(2)
	v_mfma_f32_16x16x32_bf16 v[36:39], v[132:135], v[60:63], v[36:39]
	s_waitcnt lgkmcnt(1)
	v_mfma_f32_16x16x32_bf16 v[40:43], v[136:139], v[60:63], v[40:43]
	s_waitcnt lgkmcnt(0)
	v_mfma_f32_16x16x32_bf16 v[44:47], v[140:143], v[60:63], v[44:47]
	s_waitcnt lgkmcnt(0)
	s_barrier
; __device__ __forceinline__ void attn_phase(const Params& P, char* smem_raw) {
;     ...
;     for (int ck = 0; ck < 6; ++ck) {
;       int lane_c = lane;
;       asm volatile("" : "+v"(lane_c));
;       __syncthreads();
; #pragma unroll
;       for (int i = 0; i < 4; ++i) {
;         const int idx = tid + 256 * i;
;         *reinterpret_cast<uint4*>(&sm_k[(idx >> 3) * LDSS + (idx & 7) * 8]) = kreg[i];
;         *reinterpret_cast<uint4*>(&sm_vt[(idx >> 4) * 136 + (idx & 15) * 8]) = vreg[i];
;       }
;       __syncthreads();
;       f32x4 sacc[8];
; #pragma unroll
;       for (int t8 = 0; t8 < 8; ++t8) sacc[t8] = f32x4{0.f, 0.f, 0.f, 0.f};
; #pragma unroll
;       for (int s = 0; s < 2; ++s)
; #pragma unroll
;         for (int t8 = 0; t8 < 8; ++t8) {
;           const bf16x8 kf = *reinterpret_cast<const bf16x8*>(&sm_k[(t8 * 16 + (lane_c & 15)) * LDSS + s * 32 + (lane_c >> 4) * 8]);
;           sacc[t8] = __builtin_amdgcn_mfma_f32_16x16x32_bf16(qf[s], kf, sacc[t8], 0, 0, 0);
;         }
;       if (ck < 5) {
;         ATT_ISSUE(t, ck + 1)
;       } else if (t + VGRID < 8192) {
;         ATT_ISSUE(t + VGRID, 0)
;         ATT_QLOAD(t + VGRID)
;       }
;       if (ck < 4) {
;         const float* rb0 = sm_rpb + (rs + ck * 2 - r + 7) * 31;
; #pragma unroll
;         for (int t8 = 0; t8 < 8; ++t8)
; #pragma unroll
;           for (int reg = 0; reg < 4; ++reg)
;             sacc[t8][reg] += rb0[(t8 >> 2) * 31 + dco[reg][t8 & 3]];
;       }
; #pragma unroll
;       for (int reg = 0; reg < 4; ++reg) {
;         float mx = sacc[0][reg];
; #pragma unroll
;         for (int t8 = 1; t8 < 8; ++t8) mx = fmaxf(mx, sacc[t8][reg]);
;         mx = row16_max(mx);
;         const float mnew = fmaxf(mrow[reg], mx);
;         const float alpha = __builtin_amdgcn_exp2f(mrow[reg] - mnew);
;         mrow[reg] = mnew;
;         float rsum = 0.f;
; #pragma unroll
;         for (int t8 = 0; t8 < 8; ++t8) {
;           const float p = __builtin_amdgcn_exp2f(sacc[t8][reg] - mnew);
;           rsum += p;
;           sm_p[(wid * 16 + (lane_c >> 4) * 4 + reg) * 136 + t8 * 16 + (lane_c & 15)] = f2bf(p);
;         }
;         rsum = row16_sum(rsum);
;         lrow[reg] = lrow[reg] * alpha + rsum;
; #pragma unroll
;         for (int td = 0; td < 4; ++td) o[td][reg] *= alpha;
;       }
	ds_read_b128 v[112:115], v144 offset:32768
	ds_read_b128 v[116:119], v145 offset:32768
	ds_read_b128 v[120:123], v144 offset:33280
	ds_read_b128 v[124:127], v145 offset:33280
	ds_read_b128 v[128:131], v144 offset:36864
	ds_read_b128 v[132:135], v145 offset:36864
	ds_read_b128 v[136:139], v144 offset:37376
	ds_read_b128 v[140:143], v145 offset:37376
	s_waitcnt lgkmcnt(7)
	v_mfma_f32_16x16x32_bf16 v[0:3], v[112:115], v[64:67], 0
	ds_read_b128 v[112:115], v144 offset:40960
	s_waitcnt lgkmcnt(7)
	v_mfma_f32_16x16x32_bf16 v[0:3], v[116:119], v[68:71], v[0:3]
	ds_read_b128 v[116:119], v145 offset:40960
	s_waitcnt lgkmcnt(7)
	v_mfma_f32_16x16x32_bf16 v[4:7], v[120:123], v[64:67], 0
	ds_read_b128 v[120:123], v144 offset:41472
	s_waitcnt lgkmcnt(7)
	v_mfma_f32_16x16x32_bf16 v[4:7], v[124:127], v[68:71], v[4:7]
	ds_read_b128 v[124:127], v145 offset:41472
	s_waitcnt lgkmcnt(7)
	v_mfma_f32_16x16x32_bf16 v[8:11], v[128:131], v[64:67], 0
	ds_read_b128 v[128:131], v144 offset:45056
	s_waitcnt lgkmcnt(7)
	v_mfma_f32_16x16x32_bf16 v[8:11], v[132:135], v[68:71], v[8:11]
	ds_read_b128 v[132:135], v145 offset:45056
	s_waitcnt lgkmcnt(7)
	v_mfma_f32_16x16x32_bf16 v[12:15], v[136:139], v[64:67], 0
	ds_read_b128 v[136:139], v144 offset:45568
	s_waitcnt lgkmcnt(7)
	v_mfma_f32_16x16x32_bf16 v[12:15], v[140:143], v[68:71], v[12:15]
	ds_read_b128 v[140:143], v145 offset:45568
	s_waitcnt lgkmcnt(7)
	v_mfma_f32_16x16x32_bf16 v[16:19], v[112:115], v[64:67], 0
	s_waitcnt lgkmcnt(6)
	v_mfma_f32_16x16x32_bf16 v[16:19], v[116:119], v[68:71], v[16:19]
	s_waitcnt lgkmcnt(5)
	v_mfma_f32_16x16x32_bf16 v[20:23], v[120:123], v[64:67], 0
	s_waitcnt lgkmcnt(4)
	v_mfma_f32_16x16x32_bf16 v[20:23], v[124:127], v[68:71], v[20:23]
	s_waitcnt lgkmcnt(3)
	v_mfma_f32_16x16x32_bf16 v[24:27], v[128:131], v[64:67], 0
	s_waitcnt lgkmcnt(2)
	v_mfma_f32_16x16x32_bf16 v[24:27], v[132:135], v[68:71], v[24:27]
	s_waitcnt lgkmcnt(1)
	v_mfma_f32_16x16x32_bf16 v[28:31], v[136:139], v[64:67], 0
	s_waitcnt lgkmcnt(0)
	v_mfma_f32_16x16x32_bf16 v[28:31], v[140:143], v[68:71], v[28:31]
	s_nop 7
	v_max3_f32 v203, v0, v1, v2
	v_max3_f32 v203, v203, v3, v4
	v_max3_f32 v203, v203, v5, v6
	v_max3_f32 v203, v203, v7, v8
	v_max3_f32 v203, v203, v9, v10
	v_max3_f32 v203, v203, v11, v12
	v_max3_f32 v203, v203, v13, v14
	v_max3_f32 v203, v203, v15, v16
	v_max3_f32 v203, v203, v17, v18
	v_max3_f32 v203, v203, v19, v20
	v_max3_f32 v203, v203, v21, v22
	v_max3_f32 v203, v203, v23, v24
	v_max3_f32 v203, v203, v25, v26
	v_max3_f32 v203, v203, v27, v28
	v_max3_f32 v203, v203, v29, v30
	v_max_f32_e32 v203, v203, v31
	v_mov_b32_e32 v205, v203
	s_nop 1
	v_permlane16_swap_b32_e32 v203, v205
	v_max_f32_e32 v203, v203, v205
	v_mov_b32_e32 v205, v203
	s_nop 1
	v_permlane32_swap_b32_e32 v203, v205
	v_max_f32_e32 v203, v203, v205
	v_max_f32_e32 v218, v200, v203
	v_sub_f32_e32 v220, v200, v218
	v_mov_b32_e32 v219, v218
	v_exp_f32_e32 v220, v220
	v_mov_b32_e32 v200, v218
	v_pk_add_f32 v[0:1], v[0:1], v[218:219] neg_lo:[0,1] neg_hi:[0,1]
	v_pk_add_f32 v[2:3], v[2:3], v[218:219] neg_lo:[0,1] neg_hi:[0,1]
	v_pk_add_f32 v[4:5], v[4:5], v[218:219] neg_lo:[0,1] neg_hi:[0,1]
	v_pk_add_f32 v[6:7], v[6:7], v[218:219] neg_lo:[0,1] neg_hi:[0,1]
	v_pk_add_f32 v[8:9], v[8:9], v[218:219] neg_lo:[0,1] neg_hi:[0,1]
	v_pk_add_f32 v[10:11], v[10:11], v[218:219] neg_lo:[0,1] neg_hi:[0,1]
	v_pk_add_f32 v[12:13], v[12:13], v[218:219] neg_lo:[0,1] neg_hi:[0,1]
	v_pk_add_f32 v[14:15], v[14:15], v[218:219] neg_lo:[0,1] neg_hi:[0,1]
	v_pk_add_f32 v[16:17], v[16:17], v[218:219] neg_lo:[0,1] neg_hi:[0,1]
	v_pk_add_f32 v[18:19], v[18:19], v[218:219] neg_lo:[0,1] neg_hi:[0,1]
	v_pk_add_f32 v[20:21], v[20:21], v[218:219] neg_lo:[0,1] neg_hi:[0,1]
	v_pk_add_f32 v[22:23], v[22:23], v[218:219] neg_lo:[0,1] neg_hi:[0,1]
	v_pk_add_f32 v[24:25], v[24:25], v[218:219] neg_lo:[0,1] neg_hi:[0,1]
	v_pk_add_f32 v[26:27], v[26:27], v[218:219] neg_lo:[0,1] neg_hi:[0,1]
	v_pk_add_f32 v[28:29], v[28:29], v[218:219] neg_lo:[0,1] neg_hi:[0,1]
	v_pk_add_f32 v[30:31], v[30:31], v[218:219] neg_lo:[0,1] neg_hi:[0,1]
	v_exp_f32_e32 v0, v0
	s_waitcnt vmcnt(0)
	v_exp_f32_e32 v1, v1
	ds_write_b128 v150, v[80:83] offset:0
	v_exp_f32_e32 v2, v2
	ds_write_b128 v150, v[84:87] offset:4096
	v_exp_f32_e32 v3, v3
	ds_write_b128 v150, v[88:91] offset:8192
	v_exp_f32_e32 v4, v4
	ds_write_b128 v150, v[92:95] offset:12288
	v_exp_f32_e32 v5, v5
	ds_write_b128 v151, v[96:99] offset:0
	v_exp_f32_e32 v6, v6
	ds_write_b128 v151, v[100:103] offset:4096
	v_exp_f32_e32 v7, v7
	ds_write_b128 v151, v[104:107] offset:8192
	v_exp_f32_e32 v8, v8
	ds_write_b128 v151, v[108:111] offset:12288
	v_exp_f32_e32 v9, v9
	s_add_u32 s100, s12, 0xc0000
	v_exp_f32_e32 v10, v10
	s_addc_u32 s101, s13, 0
	v_exp_f32_e32 v11, v11
	s_add_u32 s0, s14, 0x100
	v_exp_f32_e32 v12, v12
	s_addc_u32 s1, s15, 0
	v_exp_f32_e32 v13, v13
	global_load_dwordx4 v[80:83], v154, s[100:101] offset:2048
	v_exp_f32_e32 v14, v14
	global_load_dwordx4 v[96:99], v158, s[0:1]
	v_exp_f32_e32 v15, v15
	global_load_dwordx4 v[84:87], v155, s[100:101] offset:2048
	v_exp_f32_e32 v16, v16
	global_load_dwordx4 v[100:103], v159, s[0:1]
	v_exp_f32_e32 v17, v17
	global_load_dwordx4 v[88:91], v156, s[100:101] offset:2048
	v_exp_f32_e32 v18, v18
	global_load_dwordx4 v[104:107], v160, s[0:1]
	v_exp_f32_e32 v19, v19
	global_load_dwordx4 v[92:95], v157, s[100:101] offset:2048
	v_exp_f32_e32 v20, v20
	global_load_dwordx4 v[108:111], v161, s[0:1]
	v_exp_f32_e32 v21, v21
	v_exp_f32_e32 v22, v22
	v_exp_f32_e32 v23, v23
	v_exp_f32_e32 v24, v24
	v_exp_f32_e32 v25, v25
	v_exp_f32_e32 v26, v26
	v_exp_f32_e32 v27, v27
	v_exp_f32_e32 v28, v28
	v_exp_f32_e32 v29, v29
; __device__ __forceinline__ void attn_phase(const Params& P, char* smem_raw) {
;     ...
; #pragma unroll
;       for (int reg = 0; reg < 4; ++reg) {
;         float mx = sacc[0][reg];
; #pragma unroll
;         for (int t8 = 1; t8 < 8; ++t8) mx = fmaxf(mx, sacc[t8][reg]);
;         mx = row16_max(mx);
;         const float mnew = fmaxf(mrow[reg], mx);
;         const float alpha = __builtin_amdgcn_exp2f(mrow[reg] - mnew);
;         mrow[reg] = mnew;
;         float rsum = 0.f;
; #pragma unroll
;         for (int t8 = 0; t8 < 8; ++t8) {
;           const float p = __builtin_amdgcn_exp2f(sacc[t8][reg] - mnew);
;           rsum += p;
;           sm_p[(wid * 16 + (lane_c >> 4) * 4 + reg) * 136 + t8 * 16 + (lane_c & 15)] = f2bf(p);
;         }
;         rsum = row16_sum(rsum);
;         lrow[reg] = lrow[reg] * alpha + rsum;
; #pragma unroll
;         for (int td = 0; td < 4; ++td) o[td][reg] *= alpha;
;       }
;       asm volatile("s_waitcnt lgkmcnt(0)" ::: "memory");
; #pragma unroll
;       for (int s4 = 0; s4 < 4; ++s4) {
;         const bf16x8 pf = *reinterpret_cast<const bf16x8*>(&sm_p[(wid * 16 + (lane_c & 15)) * 136 + s4 * 32 + (lane_c >> 4) * 8]);
; #pragma unroll
;         for (int td = 0; td < 4; ++td) {
;           const bf16x8 vf = *reinterpret_cast<const bf16x8*>(&sm_vt[(td * 16 + (lane_c & 15)) * 136 + s4 * 32 + (lane_c >> 4) * 8]);
;           o[td] = __builtin_amdgcn_mfma_f32_16x16x32_bf16(pf, vf, o[td], 0, 0, 0);
;         }
;       }
;     }
;     u16* Ob = P.cat + ((long)b * 8192 + r * 64) * 1024 + h * 64;
; #pragma unroll
;     for (int td = 0; td < 4; ++td)
; #pragma unroll
;       for (int reg = 0; reg < 4; ++reg) {
;         const int rowl = wid * 16 + (lane >> 4) * 4 + reg;
;         Ob[(unsigned)(rowl * 1024 + td * 16 + (lane & 15))] = f2bf(o[td][reg] * __builtin_amdgcn_rcpf(lrow[reg]));
;       }
	v_exp_f32_e32 v30, v30
	v_exp_f32_e32 v31, v31
	ds_read_b128 v[112:115], v146 offset:32768
	ds_read_b128 v[116:119], v146 offset:36864
	ds_read_b128 v[120:123], v146 offset:40960
	ds_read_b128 v[124:127], v146 offset:45056
	ds_read_b128 v[128:131], v147 offset:32768
	ds_read_b128 v[132:135], v147 offset:36864
	ds_read_b128 v[136:139], v147 offset:40960
	ds_read_b128 v[140:143], v147 offset:45056
	v_mov_b32_e32 v221, v220
	v_pk_add_f32 v[222:223], v[0:1], v[2:3]
	v_pk_add_f32 v[222:223], v[222:223], v[4:5]
	v_pk_add_f32 v[222:223], v[222:223], v[6:7]
	v_pk_add_f32 v[222:223], v[222:223], v[8:9]
	v_pk_add_f32 v[222:223], v[222:223], v[10:11]
	v_pk_add_f32 v[222:223], v[222:223], v[12:13]
	v_pk_add_f32 v[222:223], v[222:223], v[14:15]
	v_pk_add_f32 v[222:223], v[222:223], v[16:17]
	v_pk_add_f32 v[222:223], v[222:223], v[18:19]
	v_pk_add_f32 v[222:223], v[222:223], v[20:21]
	v_pk_add_f32 v[222:223], v[222:223], v[22:23]
	v_pk_add_f32 v[222:223], v[222:223], v[24:25]
	v_pk_add_f32 v[222:223], v[222:223], v[26:27]
	v_pk_add_f32 v[222:223], v[222:223], v[28:29]
	v_pk_add_f32 v[222:223], v[222:223], v[30:31]
	v_pk_mul_f32 v[32:33], v[32:33], v[220:221]
	v_pk_mul_f32 v[34:35], v[34:35], v[220:221]
	v_pk_mul_f32 v[36:37], v[36:37], v[220:221]
	v_pk_mul_f32 v[38:39], v[38:39], v[220:221]
	v_pk_mul_f32 v[40:41], v[40:41], v[220:221]
	v_pk_mul_f32 v[42:43], v[42:43], v[220:221]
	v_pk_mul_f32 v[44:45], v[44:45], v[220:221]
	v_pk_mul_f32 v[46:47], v[46:47], v[220:221]
	v_add_f32_e32 v203, v222, v223
	v_fma_f32 v201, v201, v220, v203
	v_cvt_pk_bf16_f32 v48, v0, v1
	v_cvt_pk_bf16_f32 v49, v2, v3
	v_cvt_pk_bf16_f32 v50, v4, v5
	v_cvt_pk_bf16_f32 v51, v6, v7
	v_cvt_pk_bf16_f32 v52, v8, v9
	v_cvt_pk_bf16_f32 v53, v10, v11
	v_cvt_pk_bf16_f32 v54, v12, v13
	v_cvt_pk_bf16_f32 v55, v14, v15
	v_cvt_pk_bf16_f32 v56, v16, v17
	v_cvt_pk_bf16_f32 v57, v18, v19
	v_cvt_pk_bf16_f32 v58, v20, v21
	v_cvt_pk_bf16_f32 v59, v22, v23
	v_cvt_pk_bf16_f32 v60, v24, v25
	v_cvt_pk_bf16_f32 v61, v26, v27
	v_cvt_pk_bf16_f32 v62, v28, v29
	v_cvt_pk_bf16_f32 v63, v30, v31
	s_waitcnt lgkmcnt(7)
	v_mfma_f32_16x16x32_bf16 v[32:35], v[112:115], v[48:51], v[32:35]
	ds_read_b128 v[112:115], v148 offset:32768
	s_waitcnt lgkmcnt(7)
	v_mfma_f32_16x16x32_bf16 v[36:39], v[116:119], v[48:51], v[36:39]
	ds_read_b128 v[116:119], v148 offset:36864
	s_waitcnt lgkmcnt(7)
	v_mfma_f32_16x16x32_bf16 v[40:43], v[120:123], v[48:51], v[40:43]
	ds_read_b128 v[120:123], v148 offset:40960
	s_waitcnt lgkmcnt(7)
	v_mfma_f32_16x16x32_bf16 v[44:47], v[124:127], v[48:51], v[44:47]
	ds_read_b128 v[124:127], v148 offset:45056
	s_waitcnt lgkmcnt(7)
	v_mfma_f32_16x16x32_bf16 v[32:35], v[128:131], v[52:55], v[32:35]
	ds_read_b128 v[128:131], v149 offset:32768
	s_waitcnt lgkmcnt(7)
	v_mfma_f32_16x16x32_bf16 v[36:39], v[132:135], v[52:55], v[36:39]
	ds_read_b128 v[132:135], v149 offset:36864
	s_waitcnt lgkmcnt(7)
	v_mfma_f32_16x16x32_bf16 v[40:43], v[136:139], v[52:55], v[40:43]
	ds_read_b128 v[136:139], v149 offset:40960
	s_waitcnt lgkmcnt(7)
	v_mfma_f32_16x16x32_bf16 v[44:47], v[140:143], v[52:55], v[44:47]
	ds_read_b128 v[140:143], v149 offset:45056
	s_waitcnt lgkmcnt(7)
	v_mfma_f32_16x16x32_bf16 v[32:35], v[112:115], v[56:59], v[32:35]
	s_waitcnt lgkmcnt(6)
	v_mfma_f32_16x16x32_bf16 v[36:39], v[116:119], v[56:59], v[36:39]
	s_waitcnt lgkmcnt(5)
	v_mfma_f32_16x16x32_bf16 v[40:43], v[120:123], v[56:59], v[40:43]
	s_waitcnt lgkmcnt(4)
	v_mfma_f32_16x16x32_bf16 v[44:47], v[124:127], v[56:59], v[44:47]
	s_waitcnt lgkmcnt(3)
	v_mfma_f32_16x16x32_bf16 v[32:35], v[128:131], v[60:63], v[32:35]
	s_waitcnt lgkmcnt(2)
	v_mfma_f32_16x16x32_bf16 v[36:39], v[132:135], v[60:63], v[36:39]
	s_waitcnt lgkmcnt(1)
	v_mfma_f32_16x16x32_bf16 v[40:43], v[136:139], v[60:63], v[40:43]
	s_waitcnt lgkmcnt(0)
	v_mfma_f32_16x16x32_bf16 v[44:47], v[140:143], v[60:63], v[44:47]
	ds_read_b32 v0, v184 offset:384
	ds_read_b32 v1, v185 offset:384
	ds_read_b32 v2, v186 offset:384
	ds_read_b32 v3, v187 offset:384
	ds_read_b32 v4, v188 offset:384
	ds_read_b32 v5, v189 offset:384
	ds_read_b32 v6, v190 offset:384
	ds_read_b32 v7, v191 offset:384
	ds_read_b32 v8, v192 offset:384
	ds_read_b32 v9, v193 offset:384
	ds_read_b32 v10, v194 offset:384
	ds_read_b32 v11, v195 offset:384
	ds_read_b32 v12, v196 offset:384
	ds_read_b32 v13, v197 offset:384
	ds_read_b32 v14, v198 offset:384
	ds_read_b32 v15, v199 offset:384
	ds_read_b32 v16, v184 offset:512
	ds_read_b32 v17, v185 offset:512
	ds_read_b32 v18, v186 offset:512
	ds_read_b32 v19, v187 offset:512
	ds_read_b32 v20, v188 offset:512
	ds_read_b32 v21, v189 offset:512
	ds_read_b32 v22, v190 offset:512
	ds_read_b32 v23, v191 offset:512
	ds_read_b32 v24, v192 offset:512
	ds_read_b32 v25, v193 offset:512
	ds_read_b32 v26, v194 offset:512
	ds_read_b32 v27, v195 offset:512
	ds_read_b32 v28, v196 offset:512
	ds_read_b32 v29, v197 offset:512
	ds_read_b32 v30, v198 offset:512
	ds_read_b32 v31, v199 offset:512
	s_waitcnt lgkmcnt(0)
	v_mov_b32_e32 v205, v201
	s_nop 1
	v_permlane16_swap_b32_e32 v201, v205
	v_add_f32_e32 v201, v201, v205
	v_mov_b32_e32 v205, v201
	s_nop 1
	v_permlane32_swap_b32_e32 v201, v205
	v_add_f32_e32 v201, v201, v205
	v_rcp_f32_e32 v203, v201
	s_nop 7
	v_mul_f32_e32 v32, v32, v203
	v_mul_f32_e32 v33, v33, v203
	v_mul_f32_e32 v34, v34, v203
	v_mul_f32_e32 v35, v35, v203
	v_mul_f32_e32 v36, v36, v203
	v_mul_f32_e32 v37, v37, v203
	v_mul_f32_e32 v38, v38, v203
	v_mul_f32_e32 v39, v39, v203
	v_mul_f32_e32 v40, v40, v203
	v_mul_f32_e32 v41, v41, v203
	v_mul_f32_e32 v42, v42, v203
	v_mul_f32_e32 v43, v43, v203
	v_mul_f32_e32 v44, v44, v203
	v_mul_f32_e32 v45, v45, v203
	v_mul_f32_e32 v46, v46, v203
	v_mul_f32_e32 v47, v47, v203
	v_cvt_pk_bf16_f32 v210, v32, v33
	v_cvt_pk_bf16_f32 v211, v34, v35
	v_cvt_pk_bf16_f32 v212, v36, v37
	v_cvt_pk_bf16_f32 v213, v38, v39
	v_cvt_pk_bf16_f32 v214, v40, v41
	v_cvt_pk_bf16_f32 v215, v42, v43
	v_cvt_pk_bf16_f32 v216, v44, v45
	v_cvt_pk_bf16_f32 v217, v46, v47
	global_store_dwordx2 v167, v[210:211], s[98:99] offset:0
	global_store_dwordx2 v167, v[212:213], s[98:99] offset:32
	global_store_dwordx2 v167, v[214:215], s[98:99] offset:64
	global_store_dwordx2 v167, v[216:217], s[98:99] offset:96
	v_mov_b32_e32 v200, 0xf149f2ca
	v_mov_b32_e32 v201, 0
	v_mov_b32_e32 v32, 0
	v_mov_b32_e32 v33, 0
	v_mov_b32_e32 v34, 0
	v_mov_b32_e32 v35, 0
	v_mov_b32_e32 v36, 0
	v_mov_b32_e32 v37, 0
	v_mov_b32_e32 v38, 0
	v_mov_b32_e32 v39, 0
	v_mov_b32_e32 v40, 0
	v_mov_b32_e32 v41, 0
	v_mov_b32_e32 v42, 0
	v_mov_b32_e32 v43, 0
	v_mov_b32_e32 v44, 0
	v_mov_b32_e32 v45, 0
	v_mov_b32_e32 v46, 0
	v_mov_b32_e32 v47, 0
	v_mov_b32_e32 v64, v72
	v_mov_b32_e32 v65, v73
	v_mov_b32_e32 v66, v74
	v_mov_b32_e32 v67, v75
	v_mov_b32_e32 v68, v76
	v_mov_b32_e32 v69, v77
	v_mov_b32_e32 v70, v78
	v_mov_b32_e32 v71, v79
	s_add_u32 s3, s3, 1
	s_and_b32 s0, s3, 0xff
	s_cmp_lt_u32 s0, 16
	s_cbranch_scc1 .Lmy_att_tile
	s_waitcnt vmcnt(0)
	s_branch .LBB0_1501
